# combine 4x unroll all-loads-first; PO2 to d_out; scan pass2 from regs; scan blocks skip combine; P7 ss2 loads hoisted
# speedup vs baseline: 1.0025x; 1.0025x over previous
; #define LAS __attribute__((address_space(3)))
; __device__ __forceinline__ unsigned pk2(float lo, float hi) { f32x2_t v = {lo, hi}; bf16x2_t b = __builtin_convertvector(v, bf16x2_t); return __builtin_bit_cast(unsigned, b); }
; #define LBAR() do { asm volatile("s_waitcnt lgkmcnt(0)" ::: "memory"); __builtin_amdgcn_s_barrier(); asm volatile("" ::: "memory"); } while (0)
; __device__ __forceinline__ s16x4 vtr(const LAS unsigned char* p) { return __builtin_bit_cast(s16x4, __builtin_amdgcn_ds_read_tr16_b64_v4i16((LAS v4i16_t*)p)); }
; __device__ __forceinline__ void attn_phase(LAS unsigned char* lds, const bf16* __restrict__ Q, const bf16* __restrict__ Kb, const bf16* __restrict__ Vb, unsigned char* ws, float* PM, int tid, int wave, int lane) {
;     ...
;             for (int s2 = 0; s2 < 2; ++s2) { pw[i][s2].x = pk2(sacc[i][8 * s2], sacc[i][8 * s2 + 1]); pw[i][s2].y = pk2(sacc[i][8 * s2 + 2], sacc[i][8 * s2 + 3]); pw[i][s2].z = pk2(sacc[i][8 * s2 + 4], sacc[i][8 * s2 + 5]); pw[i][s2].w = pk2(sacc[i][8 * s2 + 6], sacc[i][8 * s2 + 7]); }
;         }
;         { auto rr = __builtin_amdgcn_permlane32_swap(__float_as_uint(l), __float_as_uint(l), false, false); l = __uint_as_float(rr[0]) + __uint_as_float(rr[1]); }
;         LBAR();
;         ATT_STAGE_WRITE(VROW);
;         LBAR();
;         const AttnItem C = I;
;         const int nxt = it + (int)gridDim.x; const bool more = nxt < 1536;
;         if (more) { I = attn_decode(nxt); ATT_STAGE_LOAD(Kb, I); ATT_QLOAD(I); }
;         f32x16 oacc[4];
; #pragma unroll
;         for (int i = 0; i < 4; ++i)
; #pragma unroll
;             for (int e = 0; e < 16; ++e) oacc[i][e] = 0.f;
;         const LAS unsigned char* vbase = lds + (32 * wave + 4 * h + ((lane & 15) >> 2)) * VROW + (16 * ((lane >> 4) & 1) + 4 * (lane & 3)) * 2;
; #pragma unroll
;         for (int i = 0; i < 5; ++i)
; #pragma unroll
;             for (int s2 = 0; s2 < 2; ++s2)
; #pragma unroll
;                 for (int db = 0; db < 4; ++db) {
;                     const s16x4 lo = vtr(vbase + (32 * i + 16 * s2) * VROW + db * 64), hi = vtr(vbase + (32 * i + 16 * s2 + 8) * VROW + db * 64);
;                     const bf16x8 av = {lo[0], lo[1], lo[2], lo[3], hi[0], hi[1], hi[2], hi[3]};
;                     oacc[db] = __builtin_amdgcn_mfma_f32_32x32x16_bf16(av, __builtin_bit_cast(bf16x8, pw[i][s2]), oacc[db], 0, 0, 0);
;                 }
.LBB0_594:
	v_cvt_pk_bf16_f32 v0, v4, v5
	v_cvt_pk_bf16_f32 v1, v6, v7
	ds_read_b64_tr_b16 v[4:5], v211
	ds_read_b64_tr_b16 v[6:7], v211 offset:2560
	v_cvt_pk_bf16_f32 v2, v8, v9
	v_cvt_pk_bf16_f32 v3, v10, v11
	v_cvt_pk_bf16_f32 v166, v48, v49
	v_cvt_pk_bf16_f32 v167, v50, v51
	v_cvt_pk_bf16_f32 v76, v52, v53
	v_cvt_pk_bf16_f32 v77, v54, v55
	v_cvt_pk_bf16_f32 v78, v56, v57
	v_cvt_pk_bf16_f32 v79, v58, v59
	v_cvt_pk_bf16_f32 v72, v60, v61
	v_cvt_pk_bf16_f32 v73, v62, v63
	s_waitcnt lgkmcnt(0)
	v_mfma_f32_32x32x16_bf16 v[48:63], v[4:7], v[0:3], 0
	ds_read_b64_tr_b16 v[4:5], v211 offset:64
	ds_read_b64_tr_b16 v[6:7], v211 offset:2624
	v_cvt_pk_bf16_f32 v174, v32, v33
	v_cvt_pk_bf16_f32 v175, v34, v35
	v_cvt_pk_bf16_f32 v168, v36, v37
	v_cvt_pk_bf16_f32 v169, v38, v39
	v_cvt_pk_bf16_f32 v170, v40, v41
	v_cvt_pk_bf16_f32 v171, v42, v43
	v_cvt_pk_bf16_f32 v164, v44, v45
	v_cvt_pk_bf16_f32 v165, v46, v47
	s_waitcnt lgkmcnt(0)
	v_mfma_f32_32x32x16_bf16 v[32:47], v[4:7], v[0:3], 0
	ds_read_b64_tr_b16 v[4:5], v211 offset:128
	ds_read_b64_tr_b16 v[6:7], v211 offset:2688
	v_cvt_pk_bf16_f32 v182, v16, v17
	v_cvt_pk_bf16_f32 v183, v18, v19
	v_cvt_pk_bf16_f32 v176, v20, v21
	v_cvt_pk_bf16_f32 v177, v22, v23
	v_cvt_pk_bf16_f32 v178, v24, v25
	v_cvt_pk_bf16_f32 v179, v26, v27
	v_cvt_pk_bf16_f32 v172, v28, v29
	v_cvt_pk_bf16_f32 v173, v30, v31
	v_cvt_pk_bf16_f32 v74, v64, v65
	v_cvt_pk_bf16_f32 v68, v68, v69
	v_cvt_pk_bf16_f32 v69, v70, v71
	v_cvt_pk_bf16_f32 v70, v197, v232
	v_cvt_pk_bf16_f32 v71, v233, v234
	v_cvt_pk_bf16_f32 v64, v235, v236
	s_waitcnt lgkmcnt(0)
	v_mfma_f32_32x32x16_bf16 v[16:31], v[4:7], v[0:3], 0
	ds_read_b64_tr_b16 v[4:5], v211 offset:192
	ds_read_b64_tr_b16 v[6:7], v211 offset:2752
	ds_read_b64_tr_b16 v[232:233], v211 offset:5120
	ds_read_b64_tr_b16 v[234:235], v211 offset:7680
	v_cvt_pk_bf16_f32 v180, v12, v13
	v_cvt_pk_bf16_f32 v181, v14, v15
	v_cvt_pk_bf16_f32 v75, v66, v67
	v_cvt_pk_bf16_f32 v65, v237, v238
	v_cvt_pk_bf16_f32 v66, v239, v240
	s_waitcnt lgkmcnt(0)
	v_mfma_f32_32x32x16_bf16 v[48:63], v[232:235], v[180:183], v[48:63]
	ds_read_b64_tr_b16 v[232:233], v211 offset:5184
	ds_read_b64_tr_b16 v[234:235], v211 offset:7744
	v_cvt_pk_bf16_f32 v67, v241, v242
	v_add_f32_e32 v197, v243, v244
	s_lshl_b32 s0, s93, 7
	s_waitcnt lgkmcnt(0)
	v_mfma_f32_32x32x16_bf16 v[32:47], v[232:235], v[180:183], v[32:47]
	ds_read_b64_tr_b16 v[232:233], v211 offset:5248
	ds_read_b64_tr_b16 v[234:235], v211 offset:7808
	v_mfma_f32_32x32x16_bf16 v[0:15], v[4:7], v[0:3], 0
	s_waitcnt lgkmcnt(0)
	v_mfma_f32_32x32x16_bf16 v[16:31], v[232:235], v[180:183], v[16:31]
	ds_read_b64_tr_b16 v[232:233], v211 offset:5312
	ds_read_b64_tr_b16 v[234:235], v211 offset:7872
	s_waitcnt lgkmcnt(0)
	v_mfma_f32_32x32x16_bf16 v[0:15], v[232:235], v[180:183], v[0:15]
	ds_read_b64_tr_b16 v[180:181], v211 offset:10240
	ds_read_b64_tr_b16 v[182:183], v211 offset:12800
	s_waitcnt lgkmcnt(0)
	v_mfma_f32_32x32x16_bf16 v[48:63], v[180:183], v[176:179], v[48:63]
	ds_read_b64_tr_b16 v[180:181], v211 offset:10304
	ds_read_b64_tr_b16 v[182:183], v211 offset:12864
	s_waitcnt lgkmcnt(0)
	v_mfma_f32_32x32x16_bf16 v[32:47], v[180:183], v[176:179], v[32:47]
	ds_read_b64_tr_b16 v[180:181], v211 offset:10368
	ds_read_b64_tr_b16 v[182:183], v211 offset:12928
	s_waitcnt lgkmcnt(0)
	v_mfma_f32_32x32x16_bf16 v[16:31], v[180:183], v[176:179], v[16:31]
	ds_read_b64_tr_b16 v[180:181], v211 offset:10432
	ds_read_b64_tr_b16 v[182:183], v211 offset:12992
	s_waitcnt lgkmcnt(0)
	v_mfma_f32_32x32x16_bf16 v[0:15], v[180:183], v[176:179], v[0:15]
	ds_read_b64_tr_b16 v[176:177], v211 offset:15360
	ds_read_b64_tr_b16 v[178:179], v211 offset:17920
	s_waitcnt lgkmcnt(0)
	v_mfma_f32_32x32x16_bf16 v[48:63], v[176:179], v[172:175], v[48:63]
	ds_read_b64_tr_b16 v[176:177], v211 offset:15424
	ds_read_b64_tr_b16 v[178:179], v211 offset:17984
	s_waitcnt lgkmcnt(0)
	v_mfma_f32_32x32x16_bf16 v[32:47], v[176:179], v[172:175], v[32:47]
	ds_read_b64_tr_b16 v[176:177], v211 offset:15488
	ds_read_b64_tr_b16 v[178:179], v211 offset:18048
	s_waitcnt lgkmcnt(0)
	v_mfma_f32_32x32x16_bf16 v[16:31], v[176:179], v[172:175], v[16:31]
	ds_read_b64_tr_b16 v[176:177], v211 offset:15552
	ds_read_b64_tr_b16 v[178:179], v211 offset:18112
	s_waitcnt lgkmcnt(0)
	v_mfma_f32_32x32x16_bf16 v[0:15], v[176:179], v[172:175], v[0:15]
	ds_read_b64_tr_b16 v[172:173], v211 offset:20480
	ds_read_b64_tr_b16 v[174:175], v211 offset:23040
	s_waitcnt lgkmcnt(0)
	v_mfma_f32_32x32x16_bf16 v[48:63], v[172:175], v[168:171], v[48:63]
	ds_read_b64_tr_b16 v[172:173], v211 offset:20544
	ds_read_b64_tr_b16 v[174:175], v211 offset:23104
	s_waitcnt lgkmcnt(0)
	v_mfma_f32_32x32x16_bf16 v[32:47], v[172:175], v[168:171], v[32:47]
	ds_read_b64_tr_b16 v[172:173], v211 offset:20608
	ds_read_b64_tr_b16 v[174:175], v211 offset:23168
	s_waitcnt lgkmcnt(0)
	v_mfma_f32_32x32x16_bf16 v[16:31], v[172:175], v[168:171], v[16:31]
	ds_read_b64_tr_b16 v[172:173], v211 offset:20672
	ds_read_b64_tr_b16 v[174:175], v211 offset:23232
	s_waitcnt lgkmcnt(0)
	v_mfma_f32_32x32x16_bf16 v[0:15], v[172:175], v[168:171], v[0:15]
	ds_read_b64_tr_b16 v[168:169], v211 offset:25600
	ds_read_b64_tr_b16 v[170:171], v211 offset:28160
	s_waitcnt lgkmcnt(0)
	v_mfma_f32_32x32x16_bf16 v[48:63], v[168:171], v[164:167], v[48:63]
	ds_read_b64_tr_b16 v[168:169], v211 offset:25664
	ds_read_b64_tr_b16 v[170:171], v211 offset:28224
	s_waitcnt lgkmcnt(0)
	v_mfma_f32_32x32x16_bf16 v[32:47], v[168:171], v[164:167], v[32:47]
	ds_read_b64_tr_b16 v[168:169], v211 offset:25728
	ds_read_b64_tr_b16 v[170:171], v211 offset:28288
	s_waitcnt lgkmcnt(0)
; __device__ __forceinline__ s16x4 vtr(const LAS unsigned char* p) { return __builtin_bit_cast(s16x4, __builtin_amdgcn_ds_read_tr16_b64_v4i16((LAS v4i16_t*)p)); }
; __device__ __forceinline__ void attn_phase(LAS unsigned char* lds, const bf16* __restrict__ Q, const bf16* __restrict__ Kb, const bf16* __restrict__ Vb, unsigned char* ws, float* PM, int tid, int wave, int lane) {
;     ...
; #pragma unroll
;         for (int i = 0; i < 5; ++i)
; #pragma unroll
;             for (int s2 = 0; s2 < 2; ++s2)
; #pragma unroll
;                 for (int db = 0; db < 4; ++db) {
;                     const s16x4 lo = vtr(vbase + (32 * i + 16 * s2) * VROW + db * 64), hi = vtr(vbase + (32 * i + 16 * s2 + 8) * VROW + db * 64);
;                     const bf16x8 av = {lo[0], lo[1], lo[2], lo[3], hi[0], hi[1], hi[2], hi[3]};
;                     oacc[db] = __builtin_amdgcn_mfma_f32_32x32x16_bf16(av, __builtin_bit_cast(bf16x8, pw[i][s2]), oacc[db], 0, 0, 0);
;                 }
	v_mfma_f32_32x32x16_bf16 v[16:31], v[168:171], v[164:167], v[16:31]
	ds_read_b64_tr_b16 v[168:169], v211 offset:25792
	ds_read_b64_tr_b16 v[170:171], v211 offset:28352
	s_waitcnt lgkmcnt(0)
	v_mfma_f32_32x32x16_bf16 v[0:15], v[168:171], v[164:167], v[0:15]
	ds_read_b64_tr_b16 v[164:165], v211 offset:30720
	ds_read_b64_tr_b16 v[166:167], v211 offset:33280
	s_waitcnt lgkmcnt(0)
	v_mfma_f32_32x32x16_bf16 v[48:63], v[164:167], v[76:79], v[48:63]
	ds_read_b64_tr_b16 v[164:165], v211 offset:30784
	ds_read_b64_tr_b16 v[166:167], v211 offset:33344
	s_waitcnt lgkmcnt(0)
	v_mfma_f32_32x32x16_bf16 v[32:47], v[164:167], v[76:79], v[32:47]
	ds_read_b64_tr_b16 v[164:165], v211 offset:30848
	ds_read_b64_tr_b16 v[166:167], v211 offset:33408
	s_waitcnt lgkmcnt(0)
	v_mfma_f32_32x32x16_bf16 v[16:31], v[164:167], v[76:79], v[16:31]
	ds_read_b64_tr_b16 v[164:165], v211 offset:30912
	ds_read_b64_tr_b16 v[166:167], v211 offset:33472
	s_waitcnt lgkmcnt(0)
	v_mfma_f32_32x32x16_bf16 v[0:15], v[164:167], v[76:79], v[0:15]
	ds_read_b64_tr_b16 v[76:77], v211 offset:35840
	ds_read_b64_tr_b16 v[78:79], v211 offset:38400
	s_waitcnt lgkmcnt(0)
	v_mfma_f32_32x32x16_bf16 v[48:63], v[76:79], v[72:75], v[48:63]
	ds_read_b64_tr_b16 v[76:77], v211 offset:35904
	ds_read_b64_tr_b16 v[78:79], v211 offset:38464
	s_waitcnt lgkmcnt(0)
	v_mfma_f32_32x32x16_bf16 v[32:47], v[76:79], v[72:75], v[32:47]
	ds_read_b64_tr_b16 v[76:77], v211 offset:35968
	ds_read_b64_tr_b16 v[78:79], v211 offset:38528
	s_waitcnt lgkmcnt(0)
	v_mfma_f32_32x32x16_bf16 v[16:31], v[76:79], v[72:75], v[16:31]
	ds_read_b64_tr_b16 v[76:77], v211 offset:36032
	ds_read_b64_tr_b16 v[78:79], v211 offset:38592
	s_waitcnt lgkmcnt(0)
	v_mfma_f32_32x32x16_bf16 v[0:15], v[76:79], v[72:75], v[0:15]
	ds_read_b64_tr_b16 v[72:73], v211 offset:40960
	ds_read_b64_tr_b16 v[74:75], v211 offset:43520
	s_waitcnt lgkmcnt(0)
	v_mfma_f32_32x32x16_bf16 v[48:63], v[72:75], v[68:71], v[48:63]
	ds_read_b64_tr_b16 v[72:73], v211 offset:41024
	ds_read_b64_tr_b16 v[74:75], v211 offset:43584
	s_waitcnt lgkmcnt(0)
	v_mfma_f32_32x32x16_bf16 v[32:47], v[72:75], v[68:71], v[32:47]
	ds_read_b64_tr_b16 v[72:73], v211 offset:41088
	ds_read_b64_tr_b16 v[74:75], v211 offset:43648
	s_waitcnt lgkmcnt(0)
	v_mfma_f32_32x32x16_bf16 v[16:31], v[72:75], v[68:71], v[16:31]
	ds_read_b64_tr_b16 v[72:73], v211 offset:41152
	ds_read_b64_tr_b16 v[74:75], v211 offset:43712
	s_waitcnt lgkmcnt(0)
	v_mfma_f32_32x32x16_bf16 v[0:15], v[72:75], v[68:71], v[0:15]
	ds_read_b64_tr_b16 v[68:69], v211 offset:46080
	ds_read_b64_tr_b16 v[70:71], v211 offset:48640
	s_waitcnt lgkmcnt(0)
	v_mfma_f32_32x32x16_bf16 v[48:63], v[68:71], v[64:67], v[48:63]
	ds_read_b64_tr_b16 v[68:69], v211 offset:46144
	ds_read_b64_tr_b16 v[70:71], v211 offset:48704
	s_waitcnt lgkmcnt(0)
	v_mfma_f32_32x32x16_bf16 v[32:47], v[68:71], v[64:67], v[32:47]
	ds_read_b64_tr_b16 v[68:69], v211 offset:46208
	ds_read_b64_tr_b16 v[70:71], v211 offset:48768
	s_waitcnt lgkmcnt(0)
	v_mfma_f32_32x32x16_bf16 v[16:31], v[68:71], v[64:67], v[16:31]
	ds_read_b64_tr_b16 v[68:69], v211 offset:46272
	ds_read_b64_tr_b16 v[70:71], v211 offset:48832
	s_waitcnt lgkmcnt(0)
; __device__ __forceinline__ unsigned pk2(float lo, float hi) { f32x2_t v = {lo, hi}; bf16x2_t b = __builtin_convertvector(v, bf16x2_t); return __builtin_bit_cast(unsigned, b); }
; __device__ __forceinline__ void attn_phase(LAS unsigned char* lds, const bf16* __restrict__ Q, const bf16* __restrict__ Kb, const bf16* __restrict__ Vb, unsigned char* ws, float* PM, int tid, int wave, int lane) {
;     ...
;                     oacc[db] = __builtin_amdgcn_mfma_f32_32x32x16_bf16(av, __builtin_bit_cast(bf16x8, pw[i][s2]), oacc[db], 0, 0, 0);
;                 }
;         const float inv = 1.f / l;
;         const size_t qpos = (size_t)(C.lq0 + 32 * wave + r) * C.d + C.res;
;     ...
; #pragma unroll
;         for (int db = 0; db < 4; ++db)
; #pragma unroll
;             for (int ep = 0; ep < 2; ++ep) {
;                 const int e0 = 2 * ep, e1 = 2 * ep + 1;
;                 unsigned ax = pk2(oacc[db][4 * e0] * inv, oacc[db][4 * e0 + 1] * inv), ay = pk2(oacc[db][4 * e0 + 2] * inv, oacc[db][4 * e0 + 3] * inv);
;                 unsigned bx = pk2(oacc[db][4 * e1] * inv, oacc[db][4 * e1 + 1] * inv), by = pk2(oacc[db][4 * e1 + 2] * inv, oacc[db][4 * e1 + 3] * inv);
;                 { auto rx = __builtin_amdgcn_permlane32_swap(ax, bx, false, false); ax = rx[0]; bx = rx[1]; }
;                 { auto ry = __builtin_amdgcn_permlane32_swap(ay, by, false, false); ay = ry[0]; by = ry[1]; }
;                 u32x4 o = {ax, ay, bx, by};
;                 *(u32x4*)(po + 16 * (4 * db + e0)) = o;
;             }
	v_mfma_f32_32x32x16_bf16 v[0:15], v[68:71], v[64:67], v[0:15]
	v_div_scale_f32 v64, s[8:9], v197, v197, 1.0
	v_rcp_f32_e32 v65, v64
	s_nop 0
	v_fma_f32 v66, -v64, v65, 1.0
	v_fmac_f32_e32 v65, v66, v65
	v_div_scale_f32 v66, vcc, 1.0, v197, 1.0
	v_mul_f32_e32 v67, v66, v65
	v_fma_f32 v68, -v64, v67, v66
	v_fmac_f32_e32 v67, v68, v65
	v_fma_f32 v64, -v64, v67, v66
	v_div_fmas_f32 v64, v64, v65, v67
	v_div_fixup_f32 v66, v64, v197, 1.0
	v_add_u32_e32 v67, s85, v210
	v_mov_b64_e32 v[64:65], s[96:97]
	v_mad_u64_u32 v[64:65], s[8:9], v67, s3, v[64:65]
	v_ashrrev_i32_e32 v69, 31, v67
	v_mov_b32_e32 v68, v65
	v_mad_u64_u32 v[68:69], s[8:9], v69, s3, v[68:69]
	s_ashr_i32 s85, s84, 31
	s_lshl_b64 s[8:9], s[84:85], 25
	s_add_u32 s1, s8, 0x1b400000
	s_addc_u32 s3, s9, 0
	s_cmp_lt_i32 s84, 2
	s_cselect_b32 s1, s1, 0x12c00000
	v_mov_b32_e32 v65, v68
	s_cselect_b32 s3, s3, 0
	s_add_u32 s8, s88, s1
	s_addc_u32 s9, s89, s3
	s_cmp_lt_i32 s84, 2
	v_readlane_b32 s1, v245, 15
	v_readlane_b32 s3, v245, 16
	s_cselect_b32 s8, s8, s1
	s_cselect_b32 s9, s9, s3
	v_lshlrev_b64 v[68:69], 11, v[64:65]
	v_pk_mul_f32 v[48:49], v[66:67], v[48:49] op_sel_hi:[0,1]
	v_pk_mul_f32 v[50:51], v[66:67], v[50:51] op_sel_hi:[0,1]
	v_pk_mul_f32 v[32:33], v[66:67], v[32:33] op_sel_hi:[0,1]
	v_pk_mul_f32 v[34:35], v[66:67], v[34:35] op_sel_hi:[0,1]
	v_pk_mul_f32 v[16:17], v[66:67], v[16:17] op_sel_hi:[0,1]
	v_pk_mul_f32 v[18:19], v[66:67], v[18:19] op_sel_hi:[0,1]
	v_pk_mul_f32 v[0:1], v[66:67], v[0:1] op_sel_hi:[0,1]
	v_pk_mul_f32 v[2:3], v[66:67], v[2:3] op_sel_hi:[0,1]
	v_lshl_add_u64 v[68:69], s[8:9], 0, v[68:69]
	s_lshl_b32 s96, s0, 1
	v_cvt_pk_bf16_f32 v48, v48, v49
	v_cvt_pk_bf16_f32 v49, v50, v51
	v_pk_mul_f32 v[50:51], v[66:67], v[52:53] op_sel_hi:[0,1]
	v_pk_mul_f32 v[52:53], v[66:67], v[54:55] op_sel_hi:[0,1]
	v_cvt_pk_bf16_f32 v32, v32, v33
	v_cvt_pk_bf16_f32 v33, v34, v35
	v_pk_mul_f32 v[34:35], v[66:67], v[36:37] op_sel_hi:[0,1]
	v_pk_mul_f32 v[36:37], v[66:67], v[38:39] op_sel_hi:[0,1]
	v_cvt_pk_bf16_f32 v16, v16, v17
	v_cvt_pk_bf16_f32 v17, v18, v19
	v_pk_mul_f32 v[18:19], v[66:67], v[20:21] op_sel_hi:[0,1]
	v_pk_mul_f32 v[20:21], v[66:67], v[22:23] op_sel_hi:[0,1]
	v_cvt_pk_bf16_f32 v0, v0, v1
	v_cvt_pk_bf16_f32 v1, v2, v3
	v_pk_mul_f32 v[2:3], v[66:67], v[4:5] op_sel_hi:[0,1]
	v_pk_mul_f32 v[4:5], v[66:67], v[6:7] op_sel_hi:[0,1]
	v_lshl_add_u64 v[68:69], v[68:69], 0, s[96:97]
	v_cvt_pk_bf16_f32 v50, v50, v51
	v_cvt_pk_bf16_f32 v51, v52, v53
	v_cvt_pk_bf16_f32 v34, v34, v35
	v_cvt_pk_bf16_f32 v35, v36, v37
	v_cvt_pk_bf16_f32 v18, v18, v19
	v_cvt_pk_bf16_f32 v19, v20, v21
	v_cvt_pk_bf16_f32 v2, v2, v3
	v_cvt_pk_bf16_f32 v3, v4, v5
	v_lshl_add_u64 v[68:69], v[68:69], 0, v[192:193]
	v_permlane32_swap_b32_e32 v48, v50
	v_permlane32_swap_b32_e32 v49, v51
	v_permlane32_swap_b32_e32 v32, v34
	v_permlane32_swap_b32_e32 v33, v35
	v_permlane32_swap_b32_e32 v16, v18
	v_permlane32_swap_b32_e32 v17, v19
	v_permlane32_swap_b32_e32 v0, v2
	v_permlane32_swap_b32_e32 v1, v3
	global_store_dwordx4 v[68:69], v[48:51], off
	global_store_dwordx4 v[68:69], v[32:35], off offset:64
	global_store_dwordx4 v[68:69], v[16:19], off offset:128
	v_pk_mul_f32 v[48:49], v[66:67], v[56:57] op_sel_hi:[0,1]
	v_pk_mul_f32 v[50:51], v[66:67], v[58:59] op_sel_hi:[0,1]
	v_pk_mul_f32 v[32:33], v[66:67], v[40:41] op_sel_hi:[0,1]
	v_pk_mul_f32 v[34:35], v[66:67], v[42:43] op_sel_hi:[0,1]
	v_pk_mul_f32 v[16:17], v[66:67], v[24:25] op_sel_hi:[0,1]
	v_pk_mul_f32 v[18:19], v[66:67], v[26:27] op_sel_hi:[0,1]
	global_store_dwordx4 v[68:69], v[0:3], off offset:192
	v_cvt_pk_bf16_f32 v48, v48, v49
	v_cvt_pk_bf16_f32 v49, v50, v51
	v_pk_mul_f32 v[0:1], v[66:67], v[8:9] op_sel_hi:[0,1]
	v_pk_mul_f32 v[2:3], v[66:67], v[10:11] op_sel_hi:[0,1]
	v_pk_mul_f32 v[50:51], v[66:67], v[60:61] op_sel_hi:[0,1]
	v_pk_mul_f32 v[52:53], v[66:67], v[62:63] op_sel_hi:[0,1]
	v_cvt_pk_bf16_f32 v32, v32, v33
	v_cvt_pk_bf16_f32 v33, v34, v35
	v_pk_mul_f32 v[34:35], v[66:67], v[44:45] op_sel_hi:[0,1]
	v_pk_mul_f32 v[36:37], v[66:67], v[46:47] op_sel_hi:[0,1]
	v_cvt_pk_bf16_f32 v16, v16, v17
	v_cvt_pk_bf16_f32 v17, v18, v19
	v_pk_mul_f32 v[18:19], v[66:67], v[28:29] op_sel_hi:[0,1]
	v_pk_mul_f32 v[20:21], v[66:67], v[30:31] op_sel_hi:[0,1]
	v_cvt_pk_bf16_f32 v0, v0, v1
	v_cvt_pk_bf16_f32 v1, v2, v3
	v_pk_mul_f32 v[2:3], v[66:67], v[12:13] op_sel_hi:[0,1]
	v_pk_mul_f32 v[4:5], v[66:67], v[14:15] op_sel_hi:[0,1]
	v_cvt_pk_bf16_f32 v50, v50, v51
	v_cvt_pk_bf16_f32 v51, v52, v53
	v_cvt_pk_bf16_f32 v34, v34, v35
	v_cvt_pk_bf16_f32 v35, v36, v37
	v_cvt_pk_bf16_f32 v18, v18, v19
	v_cvt_pk_bf16_f32 v19, v20, v21
	v_cvt_pk_bf16_f32 v2, v2, v3
	v_cvt_pk_bf16_f32 v3, v4, v5
	v_permlane32_swap_b32_e32 v48, v50
	v_permlane32_swap_b32_e32 v49, v51
	v_permlane32_swap_b32_e32 v32, v34
	v_permlane32_swap_b32_e32 v33, v35
	v_permlane32_swap_b32_e32 v16, v18
	v_permlane32_swap_b32_e32 v17, v19
	v_permlane32_swap_b32_e32 v0, v2
	v_permlane32_swap_b32_e32 v1, v3
	global_store_dwordx4 v[68:69], v[48:51], off offset:32
	global_store_dwordx4 v[68:69], v[32:35], off offset:96
	global_store_dwordx4 v[68:69], v[16:19], off offset:160
	global_store_dwordx4 v[68:69], v[0:3], off offset:224
	s_mov_b64 s[0:1], exec
	v_readlane_b32 s8, v245, 46
	v_readlane_b32 s9, v245, 47
	s_and_b64 s[8:9], s[0:1], s[8:9]
	s_mov_b64 exec, s[8:9]
	s_cbranch_execz .LBB0_573
	s_lshl_b64 s[8:9], s[84:85], 17
	v_lshl_add_u64 v[0:1], v[64:65], 3, s[8:9]
	v_readlane_b32 s8, v245, 38
	v_or_b32_e32 v0, s93, v0
	v_readlane_b32 s9, v245, 39
	s_nop 1
	v_lshl_add_u64 v[0:1], v[0:1], 3, s[8:9]
	global_store_dwordx2 v[0:1], v[196:197], off
	s_branch .LBB0_573

; #define LBAR() do { asm volatile("s_waitcnt lgkmcnt(0)" ::: "memory"); __builtin_amdgcn_s_barrier(); asm volatile("" ::: "memory"); } while (0)
; #define S5_LOAD(SR, SI, cb) do { _Pragma("unroll") for (int i = 0; i < 16; ++i) { SR[i] = sc[(size_t)((cb) + i) * 128 + n]; SI[i] = sc[(size_t)((cb) + i) * 128 + 64 + n]; } } while (0)
; #define S5_ACC(SR, SI) do { _Pragma("unroll") for (int i = 0; i < 16; ++i) { const float nhr = atr * hr - ati * hi + SR[i], nhi = atr * hi + ati * hr + SI[i]; hr = nhr; hi = nhi; } } while (0)
; #define S5_STEP(SR, SI, cb) do { _Pragma("unroll") for (int i = 0; i < 16; ++i) { \
;         hp[(size_t)((cb) + i) * 128 + n] = (bf16)f2bf(hr); hp[(size_t)((cb) + i) * 128 + 64 + n] = (bf16)f2bf(hi); \
;         const float nhr = atr * hr - ati * hi + SR[i], nhi = atr * hi + ati * hr + SI[i]; hr = nhr; hi = nhi; } } while (0)
; __device__ __forceinline__ void s5_scan_block(LAS unsigned char* lds, const Args& a, const float* __restrict__ SC, bf16* HP, int g, int wave, int lane) {
;     ...
;     float hr = 0.f, hi = 0.f;
;     for (int cb = 0; cb < 64; cb += 16) { S5_LOAD(sr0, si0, cb); S5_ACC(sr0, si0); }
;     LBAR();
;     ex[wave * 128 + n] = hr; ex[wave * 128 + 64 + n] = hi;
;     LBAR();
;     hr = 0.f; hi = 0.f;
;     for (int w = 0; w < wave; ++w) { const float er = ex[w * 128 + n], ei = ex[w * 128 + 64 + n]; const float nhr = asr * hr - asi * hi + er, nhi = asr * hi + asi * hr + ei; hr = nhr; hi = nhi; }
;     for (int cb = 0; cb < 64; cb += 16) { S5_LOAD(sr0, si0, cb); S5_STEP(sr0, si0, cb); }
.LBB0_777:
	s_lshl_b64 s[0:1], s[66:67], 17
	s_lshl_b64 s[2:3], s[4:5], 8
	s_add_u32 s0, s0, s2
	s_addc_u32 s1, s1, s3
	v_lshl_or_b32 v10, v184, 1, s0
	v_mov_b32_e32 v11, s1
	s_mov_b64 s[0:1], 0x19c00800
	v_lshl_add_u64 v[10:11], v[10:11], 0, s[0:1]
	s_lshl_b64 s[0:1], s[66:67], 18
	s_lshl_b64 s[2:3], s[4:5], 9
	s_add_u32 s0, s0, s2
	s_addc_u32 s1, s1, s3
	v_mov_b32_e32 v3, v2
	v_mov_b32_e32 v1, v0
	v_mov_b32_e32 v6, v2
	v_mov_b32_e32 v7, v0
	v_mov_b32_e32 v8, v0
	v_mov_b32_e32 v9, v2
	v_lshl_or_b32 v12, v184, 2, s0
	v_mov_b32_e32 v13, s1
	s_movk_i32 s9, 0x7fff
	s_mov_b64 s[2:3], 0x1000
	v_lshl_add_u64 v[16:17], s[88:89], 0, v[12:13]
	v_add_co_u32_e32 v16, vcc, 0x18c00000, v16
	s_nop 1
	v_addc_co_u32_e32 v17, vcc, 0, v17, vcc
	v_lshl_add_u64 v[14:15], s[88:89], 0, v[10:11]
	global_load_dword v56, v[16:17], off offset:0
	global_load_dword v57, v[16:17], off offset:256
	global_load_dword v58, v[16:17], off offset:512
	global_load_dword v59, v[16:17], off offset:768
	global_load_dword v60, v[16:17], off offset:1024
	global_load_dword v61, v[16:17], off offset:1280
	global_load_dword v62, v[16:17], off offset:1536
	global_load_dword v63, v[16:17], off offset:1792
	global_load_dword v64, v[16:17], off offset:2048
	global_load_dword v65, v[16:17], off offset:2304
	global_load_dword v66, v[16:17], off offset:2560
	global_load_dword v67, v[16:17], off offset:2816
	global_load_dword v68, v[16:17], off offset:3072
	global_load_dword v69, v[16:17], off offset:3328
	global_load_dword v70, v[16:17], off offset:3584
	global_load_dword v71, v[16:17], off offset:3840
	v_lshl_add_u64 v[16:17], v[16:17], 0, s[2:3]
	global_load_dword v72, v[16:17], off offset:0
	global_load_dword v73, v[16:17], off offset:256
	global_load_dword v74, v[16:17], off offset:512
	global_load_dword v75, v[16:17], off offset:768
	global_load_dword v76, v[16:17], off offset:1024
	global_load_dword v77, v[16:17], off offset:1280
	global_load_dword v78, v[16:17], off offset:1536
	global_load_dword v79, v[16:17], off offset:1792
	global_load_dword v80, v[16:17], off offset:2048
	global_load_dword v81, v[16:17], off offset:2304
	global_load_dword v82, v[16:17], off offset:2560
	global_load_dword v83, v[16:17], off offset:2816
	global_load_dword v84, v[16:17], off offset:3072
	global_load_dword v85, v[16:17], off offset:3328
	global_load_dword v86, v[16:17], off offset:3584
	global_load_dword v87, v[16:17], off offset:3840
	v_lshl_add_u64 v[16:17], v[16:17], 0, s[2:3]
	global_load_dword v88, v[16:17], off offset:0
	global_load_dword v89, v[16:17], off offset:256
	global_load_dword v90, v[16:17], off offset:512
	global_load_dword v91, v[16:17], off offset:768
	global_load_dword v92, v[16:17], off offset:1024
	global_load_dword v93, v[16:17], off offset:1280
	global_load_dword v94, v[16:17], off offset:1536
	global_load_dword v95, v[16:17], off offset:1792
	global_load_dword v96, v[16:17], off offset:2048
	global_load_dword v97, v[16:17], off offset:2304
	global_load_dword v98, v[16:17], off offset:2560
	global_load_dword v99, v[16:17], off offset:2816
	global_load_dword v100, v[16:17], off offset:3072
	global_load_dword v101, v[16:17], off offset:3328
	global_load_dword v102, v[16:17], off offset:3584
	global_load_dword v103, v[16:17], off offset:3840
	v_lshl_add_u64 v[16:17], v[16:17], 0, s[2:3]
	global_load_dword v104, v[16:17], off offset:0
	global_load_dword v105, v[16:17], off offset:256
	global_load_dword v106, v[16:17], off offset:512
	global_load_dword v107, v[16:17], off offset:768
	global_load_dword v108, v[16:17], off offset:1024
	global_load_dword v109, v[16:17], off offset:1280
	global_load_dword v110, v[16:17], off offset:1536
	global_load_dword v111, v[16:17], off offset:1792
	global_load_dword v112, v[16:17], off offset:2048
	global_load_dword v113, v[16:17], off offset:2304
	global_load_dword v114, v[16:17], off offset:2560
	global_load_dword v115, v[16:17], off offset:2816
	global_load_dword v116, v[16:17], off offset:3072
	global_load_dword v117, v[16:17], off offset:3328
	global_load_dword v118, v[16:17], off offset:3584
	global_load_dword v119, v[16:17], off offset:3840
	v_lshl_add_u64 v[16:17], v[16:17], 0, s[2:3]
	global_load_dword v120, v[16:17], off offset:0
	global_load_dword v121, v[16:17], off offset:256
	global_load_dword v122, v[16:17], off offset:512
	global_load_dword v123, v[16:17], off offset:768
	global_load_dword v124, v[16:17], off offset:1024
	global_load_dword v125, v[16:17], off offset:1280
	global_load_dword v126, v[16:17], off offset:1536
	global_load_dword v127, v[16:17], off offset:1792
	global_load_dword v128, v[16:17], off offset:2048
	global_load_dword v129, v[16:17], off offset:2304
	global_load_dword v130, v[16:17], off offset:2560
	global_load_dword v131, v[16:17], off offset:2816
	global_load_dword v132, v[16:17], off offset:3072
	global_load_dword v133, v[16:17], off offset:3328
	global_load_dword v134, v[16:17], off offset:3584
	global_load_dword v135, v[16:17], off offset:3840
	v_lshl_add_u64 v[16:17], v[16:17], 0, s[2:3]
	global_load_dword v136, v[16:17], off offset:0
	global_load_dword v137, v[16:17], off offset:256
	global_load_dword v138, v[16:17], off offset:512
	global_load_dword v139, v[16:17], off offset:768
	global_load_dword v140, v[16:17], off offset:1024
	global_load_dword v141, v[16:17], off offset:1280
	global_load_dword v142, v[16:17], off offset:1536
	global_load_dword v143, v[16:17], off offset:1792
	global_load_dword v144, v[16:17], off offset:2048
	global_load_dword v145, v[16:17], off offset:2304
	global_load_dword v146, v[16:17], off offset:2560
	global_load_dword v147, v[16:17], off offset:2816
; #define LBAR() do { asm volatile("s_waitcnt lgkmcnt(0)" ::: "memory"); __builtin_amdgcn_s_barrier(); asm volatile("" ::: "memory"); } while (0)
; #define S5_LOAD(SR, SI, cb) do { _Pragma("unroll") for (int i = 0; i < 16; ++i) { SR[i] = sc[(size_t)((cb) + i) * 128 + n]; SI[i] = sc[(size_t)((cb) + i) * 128 + 64 + n]; } } while (0)
; #define S5_ACC(SR, SI) do { _Pragma("unroll") for (int i = 0; i < 16; ++i) { const float nhr = atr * hr - ati * hi + SR[i], nhi = atr * hi + ati * hr + SI[i]; hr = nhr; hi = nhi; } } while (0)
; #define S5_STEP(SR, SI, cb) do { _Pragma("unroll") for (int i = 0; i < 16; ++i) { \
;         hp[(size_t)((cb) + i) * 128 + n] = (bf16)f2bf(hr); hp[(size_t)((cb) + i) * 128 + 64 + n] = (bf16)f2bf(hi); \
;         const float nhr = atr * hr - ati * hi + SR[i], nhi = atr * hi + ati * hr + SI[i]; hr = nhr; hi = nhi; } } while (0)
; __device__ __forceinline__ void s5_scan_block(LAS unsigned char* lds, const Args& a, const float* __restrict__ SC, bf16* HP, int g, int wave, int lane) {
;     ...
;     float hr = 0.f, hi = 0.f;
;     for (int cb = 0; cb < 64; cb += 16) { S5_LOAD(sr0, si0, cb); S5_ACC(sr0, si0); }
;     LBAR();
;     ex[wave * 128 + n] = hr; ex[wave * 128 + 64 + n] = hi;
;     LBAR();
;     hr = 0.f; hi = 0.f;
;     for (int w = 0; w < wave; ++w) { const float er = ex[w * 128 + n], ei = ex[w * 128 + 64 + n]; const float nhr = asr * hr - asi * hi + er, nhi = asr * hi + asi * hr + ei; hr = nhr; hi = nhi; }
;     for (int cb = 0; cb < 64; cb += 16) { S5_LOAD(sr0, si0, cb); S5_STEP(sr0, si0, cb); }
	global_load_dword v148, v[16:17], off offset:3072
	global_load_dword v149, v[16:17], off offset:3328
	global_load_dword v150, v[16:17], off offset:3584
	global_load_dword v151, v[16:17], off offset:3840
	v_lshl_add_u64 v[16:17], v[16:17], 0, s[2:3]
	global_load_dword v152, v[16:17], off offset:0
	global_load_dword v153, v[16:17], off offset:256
	global_load_dword v154, v[16:17], off offset:512
	global_load_dword v155, v[16:17], off offset:768
	global_load_dword v156, v[16:17], off offset:1024
	global_load_dword v157, v[16:17], off offset:1280
	global_load_dword v158, v[16:17], off offset:1536
	global_load_dword v159, v[16:17], off offset:1792
	global_load_dword v160, v[16:17], off offset:2048
	global_load_dword v161, v[16:17], off offset:2304
	global_load_dword v162, v[16:17], off offset:2560
	global_load_dword v163, v[16:17], off offset:2816
	global_load_dword v164, v[16:17], off offset:3072
	global_load_dword v165, v[16:17], off offset:3328
	global_load_dword v166, v[16:17], off offset:3584
	global_load_dword v167, v[16:17], off offset:3840
	v_lshl_add_u64 v[16:17], v[16:17], 0, s[2:3]
	global_load_dword v168, v[16:17], off offset:0
	global_load_dword v169, v[16:17], off offset:256
	global_load_dword v170, v[16:17], off offset:512
	global_load_dword v171, v[16:17], off offset:768
	global_load_dword v172, v[16:17], off offset:1024
	global_load_dword v173, v[16:17], off offset:1280
	global_load_dword v174, v[16:17], off offset:1536
	global_load_dword v175, v[16:17], off offset:1792
	global_load_dword v176, v[16:17], off offset:2048
	global_load_dword v177, v[16:17], off offset:2304
	global_load_dword v178, v[16:17], off offset:2560
	global_load_dword v179, v[16:17], off offset:2816
	global_load_dword v180, v[16:17], off offset:3072
	global_load_dword v181, v[16:17], off offset:3328
	global_load_dword v182, v[16:17], off offset:3584
	global_load_dword v183, v[16:17], off offset:3840
	s_waitcnt vmcnt(0)
	v_bfe_u32 v20, v4, 16, 1
	v_bfe_u32 v21, v5, 16, 1
	v_mul_f32_e32 v22, v0, v5
	v_mul_f32_e32 v23, v0, v4
	v_add3_u32 v20, v4, v20, s9
	v_add3_u32 v21, v5, v21, s9
	v_fma_f32 v22, v2, v4, -v22
	v_fma_f32 v23, v2, v5, v23
	global_store_short_d16_hi v[14:15], v20, off offset:-2048
	global_store_short_d16_hi v[14:15], v21, off offset:-1920
	v_add_f32_e32 v4, v22, v56
	v_add_f32_e32 v5, v23, v57
	v_bfe_u32 v24, v4, 16, 1
	v_bfe_u32 v25, v5, 16, 1
	v_mul_f32_e32 v26, v0, v5
	v_mul_f32_e32 v27, v0, v4
	v_add3_u32 v24, v4, v24, s9
	v_add3_u32 v25, v5, v25, s9
	v_fma_f32 v26, v2, v4, -v26
	v_fma_f32 v27, v2, v5, v27
	global_store_short_d16_hi v[14:15], v24, off offset:-1792
	global_store_short_d16_hi v[14:15], v25, off offset:-1664
	v_add_f32_e32 v4, v26, v58
	v_add_f32_e32 v5, v27, v59
	v_bfe_u32 v20, v4, 16, 1
	v_bfe_u32 v21, v5, 16, 1
	v_mul_f32_e32 v22, v0, v5
	v_mul_f32_e32 v23, v0, v4
	v_add3_u32 v20, v4, v20, s9
	v_add3_u32 v21, v5, v21, s9
	v_fma_f32 v22, v2, v4, -v22
	v_fma_f32 v23, v2, v5, v23
	global_store_short_d16_hi v[14:15], v20, off offset:-1536
	global_store_short_d16_hi v[14:15], v21, off offset:-1408
	v_add_f32_e32 v4, v22, v60
	v_add_f32_e32 v5, v23, v61
	v_bfe_u32 v24, v4, 16, 1
	v_bfe_u32 v25, v5, 16, 1
	v_mul_f32_e32 v26, v0, v5
	v_mul_f32_e32 v27, v0, v4
	v_add3_u32 v24, v4, v24, s9
	v_add3_u32 v25, v5, v25, s9
	v_fma_f32 v26, v2, v4, -v26
	v_fma_f32 v27, v2, v5, v27
	global_store_short_d16_hi v[14:15], v24, off offset:-1280
	global_store_short_d16_hi v[14:15], v25, off offset:-1152
	v_add_f32_e32 v4, v26, v62
	v_add_f32_e32 v5, v27, v63
	v_bfe_u32 v20, v4, 16, 1
	v_bfe_u32 v21, v5, 16, 1
	v_mul_f32_e32 v22, v0, v5
	v_mul_f32_e32 v23, v0, v4
	v_add3_u32 v20, v4, v20, s9
	v_add3_u32 v21, v5, v21, s9
	v_fma_f32 v22, v2, v4, -v22
	v_fma_f32 v23, v2, v5, v23
	global_store_short_d16_hi v[14:15], v20, off offset:-1024
	global_store_short_d16_hi v[14:15], v21, off offset:-896
	v_add_f32_e32 v4, v22, v64
	v_add_f32_e32 v5, v23, v65
	v_bfe_u32 v24, v4, 16, 1
	v_bfe_u32 v25, v5, 16, 1
	v_mul_f32_e32 v26, v0, v5
	v_mul_f32_e32 v27, v0, v4
	v_add3_u32 v24, v4, v24, s9
	v_add3_u32 v25, v5, v25, s9
	v_fma_f32 v26, v2, v4, -v26
	v_fma_f32 v27, v2, v5, v27
	global_store_short_d16_hi v[14:15], v24, off offset:-768
	global_store_short_d16_hi v[14:15], v25, off offset:-640
	v_add_f32_e32 v4, v26, v66
	v_add_f32_e32 v5, v27, v67
	v_bfe_u32 v20, v4, 16, 1
	v_bfe_u32 v21, v5, 16, 1
	v_mul_f32_e32 v22, v0, v5
	v_mul_f32_e32 v23, v0, v4
	v_add3_u32 v20, v4, v20, s9
	v_add3_u32 v21, v5, v21, s9
	v_fma_f32 v22, v2, v4, -v22
	v_fma_f32 v23, v2, v5, v23
	global_store_short_d16_hi v[14:15], v20, off offset:-512
	global_store_short_d16_hi v[14:15], v21, off offset:-384
	v_add_f32_e32 v4, v22, v68
	v_add_f32_e32 v5, v23, v69
	v_bfe_u32 v24, v4, 16, 1
	v_bfe_u32 v25, v5, 16, 1
	v_mul_f32_e32 v26, v0, v5
	v_mul_f32_e32 v27, v0, v4
	v_add3_u32 v24, v4, v24, s9
	v_add3_u32 v25, v5, v25, s9
	v_fma_f32 v26, v2, v4, -v26
	v_fma_f32 v27, v2, v5, v27
	global_store_short_d16_hi v[14:15], v24, off offset:-256
	global_store_short_d16_hi v[14:15], v25, off offset:-128
	v_add_f32_e32 v4, v26, v70
	v_add_f32_e32 v5, v27, v71
	v_bfe_u32 v20, v4, 16, 1
	v_bfe_u32 v21, v5, 16, 1
	v_mul_f32_e32 v22, v0, v5
	v_mul_f32_e32 v23, v0, v4
	v_add3_u32 v20, v4, v20, s9
	v_add3_u32 v21, v5, v21, s9
	v_fma_f32 v22, v2, v4, -v22
	v_fma_f32 v23, v2, v5, v23
	global_store_short_d16_hi v[14:15], v20, off
	global_store_short_d16_hi v[14:15], v21, off offset:128
	v_add_f32_e32 v4, v22, v72
	v_add_f32_e32 v5, v23, v73
	v_bfe_u32 v24, v4, 16, 1
	v_bfe_u32 v25, v5, 16, 1
	v_mul_f32_e32 v26, v0, v5
	v_mul_f32_e32 v27, v0, v4
	v_add3_u32 v24, v4, v24, s9
	v_add3_u32 v25, v5, v25, s9
; #define LBAR() do { asm volatile("s_waitcnt lgkmcnt(0)" ::: "memory"); __builtin_amdgcn_s_barrier(); asm volatile("" ::: "memory"); } while (0)
; #define S5_LOAD(SR, SI, cb) do { _Pragma("unroll") for (int i = 0; i < 16; ++i) { SR[i] = sc[(size_t)((cb) + i) * 128 + n]; SI[i] = sc[(size_t)((cb) + i) * 128 + 64 + n]; } } while (0)
; #define S5_ACC(SR, SI) do { _Pragma("unroll") for (int i = 0; i < 16; ++i) { const float nhr = atr * hr - ati * hi + SR[i], nhi = atr * hi + ati * hr + SI[i]; hr = nhr; hi = nhi; } } while (0)
; #define S5_STEP(SR, SI, cb) do { _Pragma("unroll") for (int i = 0; i < 16; ++i) { \
;         hp[(size_t)((cb) + i) * 128 + n] = (bf16)f2bf(hr); hp[(size_t)((cb) + i) * 128 + 64 + n] = (bf16)f2bf(hi); \
;         const float nhr = atr * hr - ati * hi + SR[i], nhi = atr * hi + ati * hr + SI[i]; hr = nhr; hi = nhi; } } while (0)
; __device__ __forceinline__ void s5_scan_block(LAS unsigned char* lds, const Args& a, const float* __restrict__ SC, bf16* HP, int g, int wave, int lane) {
;     ...
;     float hr = 0.f, hi = 0.f;
;     for (int cb = 0; cb < 64; cb += 16) { S5_LOAD(sr0, si0, cb); S5_ACC(sr0, si0); }
;     LBAR();
;     ex[wave * 128 + n] = hr; ex[wave * 128 + 64 + n] = hi;
;     LBAR();
;     hr = 0.f; hi = 0.f;
;     for (int w = 0; w < wave; ++w) { const float er = ex[w * 128 + n], ei = ex[w * 128 + 64 + n]; const float nhr = asr * hr - asi * hi + er, nhi = asr * hi + asi * hr + ei; hr = nhr; hi = nhi; }
;     for (int cb = 0; cb < 64; cb += 16) { S5_LOAD(sr0, si0, cb); S5_STEP(sr0, si0, cb); }
	v_fma_f32 v26, v2, v4, -v26
	v_fma_f32 v27, v2, v5, v27
	global_store_short_d16_hi v[14:15], v24, off offset:256
	global_store_short_d16_hi v[14:15], v25, off offset:384
	v_add_f32_e32 v4, v26, v74
	v_add_f32_e32 v5, v27, v75
	v_bfe_u32 v20, v4, 16, 1
	v_bfe_u32 v21, v5, 16, 1
	v_mul_f32_e32 v22, v0, v5
	v_mul_f32_e32 v23, v0, v4
	v_add3_u32 v20, v4, v20, s9
	v_add3_u32 v21, v5, v21, s9
	v_fma_f32 v22, v2, v4, -v22
	v_fma_f32 v23, v2, v5, v23
	global_store_short_d16_hi v[14:15], v20, off offset:512
	global_store_short_d16_hi v[14:15], v21, off offset:640
	v_add_f32_e32 v4, v22, v76
	v_add_f32_e32 v5, v23, v77
	v_bfe_u32 v24, v4, 16, 1
	v_bfe_u32 v25, v5, 16, 1
	v_mul_f32_e32 v26, v0, v5
	v_mul_f32_e32 v27, v0, v4
	v_add3_u32 v24, v4, v24, s9
	v_add3_u32 v25, v5, v25, s9
	v_fma_f32 v26, v2, v4, -v26
	v_fma_f32 v27, v2, v5, v27
	global_store_short_d16_hi v[14:15], v24, off offset:768
	global_store_short_d16_hi v[14:15], v25, off offset:896
	v_add_f32_e32 v4, v26, v78
	v_add_f32_e32 v5, v27, v79
	v_bfe_u32 v20, v4, 16, 1
	v_bfe_u32 v21, v5, 16, 1
	v_mul_f32_e32 v22, v0, v5
	v_mul_f32_e32 v23, v0, v4
	v_add3_u32 v20, v4, v20, s9
	v_add3_u32 v21, v5, v21, s9
	v_fma_f32 v22, v2, v4, -v22
	v_fma_f32 v23, v2, v5, v23
	global_store_short_d16_hi v[14:15], v20, off offset:1024
	global_store_short_d16_hi v[14:15], v21, off offset:1152
	v_add_f32_e32 v4, v22, v80
	v_add_f32_e32 v5, v23, v81
	v_bfe_u32 v24, v4, 16, 1
	v_bfe_u32 v25, v5, 16, 1
	v_mul_f32_e32 v26, v0, v5
	v_mul_f32_e32 v27, v0, v4
	v_add3_u32 v24, v4, v24, s9
	v_add3_u32 v25, v5, v25, s9
	v_fma_f32 v26, v2, v4, -v26
	v_fma_f32 v27, v2, v5, v27
	global_store_short_d16_hi v[14:15], v24, off offset:1280
	global_store_short_d16_hi v[14:15], v25, off offset:1408
	v_add_f32_e32 v4, v26, v82
	v_add_f32_e32 v5, v27, v83
	v_bfe_u32 v20, v4, 16, 1
	v_bfe_u32 v21, v5, 16, 1
	v_mul_f32_e32 v22, v0, v5
	v_mul_f32_e32 v23, v0, v4
	v_add3_u32 v20, v4, v20, s9
	v_add3_u32 v21, v5, v21, s9
	v_fma_f32 v22, v2, v4, -v22
	v_fma_f32 v23, v2, v5, v23
	global_store_short_d16_hi v[14:15], v20, off offset:1536
	global_store_short_d16_hi v[14:15], v21, off offset:1664
	v_add_f32_e32 v4, v22, v84
	v_add_f32_e32 v5, v23, v85
	v_bfe_u32 v24, v4, 16, 1
	v_bfe_u32 v25, v5, 16, 1
	v_mul_f32_e32 v26, v0, v5
	v_mul_f32_e32 v27, v0, v4
	v_add3_u32 v24, v4, v24, s9
	v_add3_u32 v25, v5, v25, s9
	v_fma_f32 v26, v2, v4, -v26
	v_fma_f32 v27, v2, v5, v27
	global_store_short_d16_hi v[14:15], v24, off offset:1792
	global_store_short_d16_hi v[14:15], v25, off offset:1920
	v_add_f32_e32 v4, v26, v86
	v_add_f32_e32 v5, v27, v87
	v_lshl_add_u64 v[14:15], v[14:15], 0, s[2:3]
	v_bfe_u32 v20, v4, 16, 1
	v_bfe_u32 v21, v5, 16, 1
	v_mul_f32_e32 v22, v0, v5
	v_mul_f32_e32 v23, v0, v4
	v_add3_u32 v20, v4, v20, s9
	v_add3_u32 v21, v5, v21, s9
	v_fma_f32 v22, v2, v4, -v22
	v_fma_f32 v23, v2, v5, v23
	global_store_short_d16_hi v[14:15], v20, off offset:-2048
	global_store_short_d16_hi v[14:15], v21, off offset:-1920
	v_add_f32_e32 v4, v22, v88
	v_add_f32_e32 v5, v23, v89
	v_bfe_u32 v24, v4, 16, 1
	v_bfe_u32 v25, v5, 16, 1
	v_mul_f32_e32 v26, v0, v5
	v_mul_f32_e32 v27, v0, v4
	v_add3_u32 v24, v4, v24, s9
	v_add3_u32 v25, v5, v25, s9
	v_fma_f32 v26, v2, v4, -v26
	v_fma_f32 v27, v2, v5, v27
	global_store_short_d16_hi v[14:15], v24, off offset:-1792
	global_store_short_d16_hi v[14:15], v25, off offset:-1664
	v_add_f32_e32 v4, v26, v90
	v_add_f32_e32 v5, v27, v91
	v_bfe_u32 v20, v4, 16, 1
	v_bfe_u32 v21, v5, 16, 1
	v_mul_f32_e32 v22, v0, v5
	v_mul_f32_e32 v23, v0, v4
	v_add3_u32 v20, v4, v20, s9
	v_add3_u32 v21, v5, v21, s9
	v_fma_f32 v22, v2, v4, -v22
	v_fma_f32 v23, v2, v5, v23
	global_store_short_d16_hi v[14:15], v20, off offset:-1536
	global_store_short_d16_hi v[14:15], v21, off offset:-1408
	v_add_f32_e32 v4, v22, v92
	v_add_f32_e32 v5, v23, v93
	v_bfe_u32 v24, v4, 16, 1
	v_bfe_u32 v25, v5, 16, 1
	v_mul_f32_e32 v26, v0, v5
	v_mul_f32_e32 v27, v0, v4
	v_add3_u32 v24, v4, v24, s9
	v_add3_u32 v25, v5, v25, s9
	v_fma_f32 v26, v2, v4, -v26
	v_fma_f32 v27, v2, v5, v27
	global_store_short_d16_hi v[14:15], v24, off offset:-1280
	global_store_short_d16_hi v[14:15], v25, off offset:-1152
	v_add_f32_e32 v4, v26, v94
	v_add_f32_e32 v5, v27, v95
	v_bfe_u32 v20, v4, 16, 1
	v_bfe_u32 v21, v5, 16, 1
	v_mul_f32_e32 v22, v0, v5
	v_mul_f32_e32 v23, v0, v4
	v_add3_u32 v20, v4, v20, s9
	v_add3_u32 v21, v5, v21, s9
	v_fma_f32 v22, v2, v4, -v22
	v_fma_f32 v23, v2, v5, v23
	global_store_short_d16_hi v[14:15], v20, off offset:-1024
	global_store_short_d16_hi v[14:15], v21, off offset:-896
	v_add_f32_e32 v4, v22, v96
	v_add_f32_e32 v5, v23, v97
	v_bfe_u32 v24, v4, 16, 1
	v_bfe_u32 v25, v5, 16, 1
	v_mul_f32_e32 v26, v0, v5
	v_mul_f32_e32 v27, v0, v4
	v_add3_u32 v24, v4, v24, s9
	v_add3_u32 v25, v5, v25, s9
	v_fma_f32 v26, v2, v4, -v26
	v_fma_f32 v27, v2, v5, v27
	global_store_short_d16_hi v[14:15], v24, off offset:-768
	global_store_short_d16_hi v[14:15], v25, off offset:-640
	v_add_f32_e32 v4, v26, v98
	v_add_f32_e32 v5, v27, v99
	v_bfe_u32 v20, v4, 16, 1
	v_bfe_u32 v21, v5, 16, 1
	v_mul_f32_e32 v22, v0, v5
	v_mul_f32_e32 v23, v0, v4
	v_add3_u32 v20, v4, v20, s9
	v_add3_u32 v21, v5, v21, s9
	v_fma_f32 v22, v2, v4, -v22
	v_fma_f32 v23, v2, v5, v23
	global_store_short_d16_hi v[14:15], v20, off offset:-512
	global_store_short_d16_hi v[14:15], v21, off offset:-384
	v_add_f32_e32 v4, v22, v100
	v_add_f32_e32 v5, v23, v101
	v_bfe_u32 v24, v4, 16, 1
	v_bfe_u32 v25, v5, 16, 1
	v_mul_f32_e32 v26, v0, v5
	v_mul_f32_e32 v27, v0, v4
	v_add3_u32 v24, v4, v24, s9
	v_add3_u32 v25, v5, v25, s9
	v_fma_f32 v26, v2, v4, -v26
	v_fma_f32 v27, v2, v5, v27
	global_store_short_d16_hi v[14:15], v24, off offset:-256
; #define LBAR() do { asm volatile("s_waitcnt lgkmcnt(0)" ::: "memory"); __builtin_amdgcn_s_barrier(); asm volatile("" ::: "memory"); } while (0)
; #define S5_LOAD(SR, SI, cb) do { _Pragma("unroll") for (int i = 0; i < 16; ++i) { SR[i] = sc[(size_t)((cb) + i) * 128 + n]; SI[i] = sc[(size_t)((cb) + i) * 128 + 64 + n]; } } while (0)
; #define S5_ACC(SR, SI) do { _Pragma("unroll") for (int i = 0; i < 16; ++i) { const float nhr = atr * hr - ati * hi + SR[i], nhi = atr * hi + ati * hr + SI[i]; hr = nhr; hi = nhi; } } while (0)
; #define S5_STEP(SR, SI, cb) do { _Pragma("unroll") for (int i = 0; i < 16; ++i) { \
;         hp[(size_t)((cb) + i) * 128 + n] = (bf16)f2bf(hr); hp[(size_t)((cb) + i) * 128 + 64 + n] = (bf16)f2bf(hi); \
;         const float nhr = atr * hr - ati * hi + SR[i], nhi = atr * hi + ati * hr + SI[i]; hr = nhr; hi = nhi; } } while (0)
; __device__ __forceinline__ void s5_scan_block(LAS unsigned char* lds, const Args& a, const float* __restrict__ SC, bf16* HP, int g, int wave, int lane) {
;     ...
;     float hr = 0.f, hi = 0.f;
;     for (int cb = 0; cb < 64; cb += 16) { S5_LOAD(sr0, si0, cb); S5_ACC(sr0, si0); }
;     LBAR();
;     ex[wave * 128 + n] = hr; ex[wave * 128 + 64 + n] = hi;
;     LBAR();
;     hr = 0.f; hi = 0.f;
;     for (int w = 0; w < wave; ++w) { const float er = ex[w * 128 + n], ei = ex[w * 128 + 64 + n]; const float nhr = asr * hr - asi * hi + er, nhi = asr * hi + asi * hr + ei; hr = nhr; hi = nhi; }
;     for (int cb = 0; cb < 64; cb += 16) { S5_LOAD(sr0, si0, cb); S5_STEP(sr0, si0, cb); }
	global_store_short_d16_hi v[14:15], v25, off offset:-128
	v_add_f32_e32 v4, v26, v102
	v_add_f32_e32 v5, v27, v103
	v_bfe_u32 v20, v4, 16, 1
	v_bfe_u32 v21, v5, 16, 1
	v_mul_f32_e32 v22, v0, v5
	v_mul_f32_e32 v23, v0, v4
	v_add3_u32 v20, v4, v20, s9
	v_add3_u32 v21, v5, v21, s9
	v_fma_f32 v22, v2, v4, -v22
	v_fma_f32 v23, v2, v5, v23
	global_store_short_d16_hi v[14:15], v20, off
	global_store_short_d16_hi v[14:15], v21, off offset:128
	v_add_f32_e32 v4, v22, v104
	v_add_f32_e32 v5, v23, v105
	v_bfe_u32 v24, v4, 16, 1
	v_bfe_u32 v25, v5, 16, 1
	v_mul_f32_e32 v26, v0, v5
	v_mul_f32_e32 v27, v0, v4
	v_add3_u32 v24, v4, v24, s9
	v_add3_u32 v25, v5, v25, s9
	v_fma_f32 v26, v2, v4, -v26
	v_fma_f32 v27, v2, v5, v27
	global_store_short_d16_hi v[14:15], v24, off offset:256
	global_store_short_d16_hi v[14:15], v25, off offset:384
	v_add_f32_e32 v4, v26, v106
	v_add_f32_e32 v5, v27, v107
	v_bfe_u32 v20, v4, 16, 1
	v_bfe_u32 v21, v5, 16, 1
	v_mul_f32_e32 v22, v0, v5
	v_mul_f32_e32 v23, v0, v4
	v_add3_u32 v20, v4, v20, s9
	v_add3_u32 v21, v5, v21, s9
	v_fma_f32 v22, v2, v4, -v22
	v_fma_f32 v23, v2, v5, v23
	global_store_short_d16_hi v[14:15], v20, off offset:512
	global_store_short_d16_hi v[14:15], v21, off offset:640
	v_add_f32_e32 v4, v22, v108
	v_add_f32_e32 v5, v23, v109
	v_bfe_u32 v24, v4, 16, 1
	v_bfe_u32 v25, v5, 16, 1
	v_mul_f32_e32 v26, v0, v5
	v_mul_f32_e32 v27, v0, v4
	v_add3_u32 v24, v4, v24, s9
	v_add3_u32 v25, v5, v25, s9
	v_fma_f32 v26, v2, v4, -v26
	v_fma_f32 v27, v2, v5, v27
	global_store_short_d16_hi v[14:15], v24, off offset:768
	global_store_short_d16_hi v[14:15], v25, off offset:896
	v_add_f32_e32 v4, v26, v110
	v_add_f32_e32 v5, v27, v111
	v_bfe_u32 v20, v4, 16, 1
	v_bfe_u32 v21, v5, 16, 1
	v_mul_f32_e32 v22, v0, v5
	v_mul_f32_e32 v23, v0, v4
	v_add3_u32 v20, v4, v20, s9
	v_add3_u32 v21, v5, v21, s9
	v_fma_f32 v22, v2, v4, -v22
	v_fma_f32 v23, v2, v5, v23
	global_store_short_d16_hi v[14:15], v20, off offset:1024
	global_store_short_d16_hi v[14:15], v21, off offset:1152
	v_add_f32_e32 v4, v22, v112
	v_add_f32_e32 v5, v23, v113
	v_bfe_u32 v24, v4, 16, 1
	v_bfe_u32 v25, v5, 16, 1
	v_mul_f32_e32 v26, v0, v5
	v_mul_f32_e32 v27, v0, v4
	v_add3_u32 v24, v4, v24, s9
	v_add3_u32 v25, v5, v25, s9
	v_fma_f32 v26, v2, v4, -v26
	v_fma_f32 v27, v2, v5, v27
	global_store_short_d16_hi v[14:15], v24, off offset:1280
	global_store_short_d16_hi v[14:15], v25, off offset:1408
	v_add_f32_e32 v4, v26, v114
	v_add_f32_e32 v5, v27, v115
	v_bfe_u32 v20, v4, 16, 1
	v_bfe_u32 v21, v5, 16, 1
	v_mul_f32_e32 v22, v0, v5
	v_mul_f32_e32 v23, v0, v4
	v_add3_u32 v20, v4, v20, s9
	v_add3_u32 v21, v5, v21, s9
	v_fma_f32 v22, v2, v4, -v22
	v_fma_f32 v23, v2, v5, v23
	global_store_short_d16_hi v[14:15], v20, off offset:1536
	global_store_short_d16_hi v[14:15], v21, off offset:1664
	v_add_f32_e32 v4, v22, v116
	v_add_f32_e32 v5, v23, v117
	v_bfe_u32 v24, v4, 16, 1
	v_bfe_u32 v25, v5, 16, 1
	v_mul_f32_e32 v26, v0, v5
	v_mul_f32_e32 v27, v0, v4
	v_add3_u32 v24, v4, v24, s9
	v_add3_u32 v25, v5, v25, s9
	v_fma_f32 v26, v2, v4, -v26
	v_fma_f32 v27, v2, v5, v27
	global_store_short_d16_hi v[14:15], v24, off offset:1792
	global_store_short_d16_hi v[14:15], v25, off offset:1920
	v_add_f32_e32 v4, v26, v118
	v_add_f32_e32 v5, v27, v119
	v_lshl_add_u64 v[14:15], v[14:15], 0, s[2:3]
	v_bfe_u32 v20, v4, 16, 1
	v_bfe_u32 v21, v5, 16, 1
	v_mul_f32_e32 v22, v0, v5
	v_mul_f32_e32 v23, v0, v4
	v_add3_u32 v20, v4, v20, s9
	v_add3_u32 v21, v5, v21, s9
	v_fma_f32 v22, v2, v4, -v22
	v_fma_f32 v23, v2, v5, v23
	global_store_short_d16_hi v[14:15], v20, off offset:-2048
	global_store_short_d16_hi v[14:15], v21, off offset:-1920
	v_add_f32_e32 v4, v22, v120
	v_add_f32_e32 v5, v23, v121
	v_bfe_u32 v24, v4, 16, 1
	v_bfe_u32 v25, v5, 16, 1
	v_mul_f32_e32 v26, v0, v5
	v_mul_f32_e32 v27, v0, v4
	v_add3_u32 v24, v4, v24, s9
	v_add3_u32 v25, v5, v25, s9
	v_fma_f32 v26, v2, v4, -v26
	v_fma_f32 v27, v2, v5, v27
	global_store_short_d16_hi v[14:15], v24, off offset:-1792
	global_store_short_d16_hi v[14:15], v25, off offset:-1664
	v_add_f32_e32 v4, v26, v122
	v_add_f32_e32 v5, v27, v123
	v_bfe_u32 v20, v4, 16, 1
	v_bfe_u32 v21, v5, 16, 1
	v_mul_f32_e32 v22, v0, v5
	v_mul_f32_e32 v23, v0, v4
	v_add3_u32 v20, v4, v20, s9
	v_add3_u32 v21, v5, v21, s9
	v_fma_f32 v22, v2, v4, -v22
	v_fma_f32 v23, v2, v5, v23
	global_store_short_d16_hi v[14:15], v20, off offset:-1536
	global_store_short_d16_hi v[14:15], v21, off offset:-1408
	v_add_f32_e32 v4, v22, v124
	v_add_f32_e32 v5, v23, v125
	v_bfe_u32 v24, v4, 16, 1
	v_bfe_u32 v25, v5, 16, 1
	v_mul_f32_e32 v26, v0, v5
	v_mul_f32_e32 v27, v0, v4
	v_add3_u32 v24, v4, v24, s9
	v_add3_u32 v25, v5, v25, s9
	v_fma_f32 v26, v2, v4, -v26
	v_fma_f32 v27, v2, v5, v27
	global_store_short_d16_hi v[14:15], v24, off offset:-1280
	global_store_short_d16_hi v[14:15], v25, off offset:-1152
	v_add_f32_e32 v4, v26, v126
	v_add_f32_e32 v5, v27, v127
	v_bfe_u32 v20, v4, 16, 1
	v_bfe_u32 v21, v5, 16, 1
	v_mul_f32_e32 v22, v0, v5
	v_mul_f32_e32 v23, v0, v4
	v_add3_u32 v20, v4, v20, s9
	v_add3_u32 v21, v5, v21, s9
	v_fma_f32 v22, v2, v4, -v22
	v_fma_f32 v23, v2, v5, v23
	global_store_short_d16_hi v[14:15], v20, off offset:-1024
	global_store_short_d16_hi v[14:15], v21, off offset:-896
	v_add_f32_e32 v4, v22, v128
	v_add_f32_e32 v5, v23, v129
	v_bfe_u32 v24, v4, 16, 1
	v_bfe_u32 v25, v5, 16, 1
	v_mul_f32_e32 v26, v0, v5
	v_mul_f32_e32 v27, v0, v4
	v_add3_u32 v24, v4, v24, s9
	v_add3_u32 v25, v5, v25, s9
	v_fma_f32 v26, v2, v4, -v26
	v_fma_f32 v27, v2, v5, v27
	global_store_short_d16_hi v[14:15], v24, off offset:-768
	global_store_short_d16_hi v[14:15], v25, off offset:-640
	v_add_f32_e32 v4, v26, v130
; #define LBAR() do { asm volatile("s_waitcnt lgkmcnt(0)" ::: "memory"); __builtin_amdgcn_s_barrier(); asm volatile("" ::: "memory"); } while (0)
; #define S5_LOAD(SR, SI, cb) do { _Pragma("unroll") for (int i = 0; i < 16; ++i) { SR[i] = sc[(size_t)((cb) + i) * 128 + n]; SI[i] = sc[(size_t)((cb) + i) * 128 + 64 + n]; } } while (0)
; #define S5_ACC(SR, SI) do { _Pragma("unroll") for (int i = 0; i < 16; ++i) { const float nhr = atr * hr - ati * hi + SR[i], nhi = atr * hi + ati * hr + SI[i]; hr = nhr; hi = nhi; } } while (0)
; #define S5_STEP(SR, SI, cb) do { _Pragma("unroll") for (int i = 0; i < 16; ++i) { \
;         hp[(size_t)((cb) + i) * 128 + n] = (bf16)f2bf(hr); hp[(size_t)((cb) + i) * 128 + 64 + n] = (bf16)f2bf(hi); \
;         const float nhr = atr * hr - ati * hi + SR[i], nhi = atr * hi + ati * hr + SI[i]; hr = nhr; hi = nhi; } } while (0)
; __device__ __forceinline__ void s5_scan_block(LAS unsigned char* lds, const Args& a, const float* __restrict__ SC, bf16* HP, int g, int wave, int lane) {
;     ...
;     float hr = 0.f, hi = 0.f;
;     for (int cb = 0; cb < 64; cb += 16) { S5_LOAD(sr0, si0, cb); S5_ACC(sr0, si0); }
;     LBAR();
;     ex[wave * 128 + n] = hr; ex[wave * 128 + 64 + n] = hi;
;     LBAR();
;     hr = 0.f; hi = 0.f;
;     for (int w = 0; w < wave; ++w) { const float er = ex[w * 128 + n], ei = ex[w * 128 + 64 + n]; const float nhr = asr * hr - asi * hi + er, nhi = asr * hi + asi * hr + ei; hr = nhr; hi = nhi; }
;     for (int cb = 0; cb < 64; cb += 16) { S5_LOAD(sr0, si0, cb); S5_STEP(sr0, si0, cb); }
	v_add_f32_e32 v5, v27, v131
	v_bfe_u32 v20, v4, 16, 1
	v_bfe_u32 v21, v5, 16, 1
	v_mul_f32_e32 v22, v0, v5
	v_mul_f32_e32 v23, v0, v4
	v_add3_u32 v20, v4, v20, s9
	v_add3_u32 v21, v5, v21, s9
	v_fma_f32 v22, v2, v4, -v22
	v_fma_f32 v23, v2, v5, v23
	global_store_short_d16_hi v[14:15], v20, off offset:-512
	global_store_short_d16_hi v[14:15], v21, off offset:-384
	v_add_f32_e32 v4, v22, v132
	v_add_f32_e32 v5, v23, v133
	v_bfe_u32 v24, v4, 16, 1
	v_bfe_u32 v25, v5, 16, 1
	v_mul_f32_e32 v26, v0, v5
	v_mul_f32_e32 v27, v0, v4
	v_add3_u32 v24, v4, v24, s9
	v_add3_u32 v25, v5, v25, s9
	v_fma_f32 v26, v2, v4, -v26
	v_fma_f32 v27, v2, v5, v27
	global_store_short_d16_hi v[14:15], v24, off offset:-256
	global_store_short_d16_hi v[14:15], v25, off offset:-128
	v_add_f32_e32 v4, v26, v134
	v_add_f32_e32 v5, v27, v135
	v_bfe_u32 v20, v4, 16, 1
	v_bfe_u32 v21, v5, 16, 1
	v_mul_f32_e32 v22, v0, v5
	v_mul_f32_e32 v23, v0, v4
	v_add3_u32 v20, v4, v20, s9
	v_add3_u32 v21, v5, v21, s9
	v_fma_f32 v22, v2, v4, -v22
	v_fma_f32 v23, v2, v5, v23
	global_store_short_d16_hi v[14:15], v20, off
	global_store_short_d16_hi v[14:15], v21, off offset:128
	v_add_f32_e32 v4, v22, v136
	v_add_f32_e32 v5, v23, v137
	v_bfe_u32 v24, v4, 16, 1
	v_bfe_u32 v25, v5, 16, 1
	v_mul_f32_e32 v26, v0, v5
	v_mul_f32_e32 v27, v0, v4
	v_add3_u32 v24, v4, v24, s9
	v_add3_u32 v25, v5, v25, s9
	v_fma_f32 v26, v2, v4, -v26
	v_fma_f32 v27, v2, v5, v27
	global_store_short_d16_hi v[14:15], v24, off offset:256
	global_store_short_d16_hi v[14:15], v25, off offset:384
	v_add_f32_e32 v4, v26, v138
	v_add_f32_e32 v5, v27, v139
	v_bfe_u32 v20, v4, 16, 1
	v_bfe_u32 v21, v5, 16, 1
	v_mul_f32_e32 v22, v0, v5
	v_mul_f32_e32 v23, v0, v4
	v_add3_u32 v20, v4, v20, s9
	v_add3_u32 v21, v5, v21, s9
	v_fma_f32 v22, v2, v4, -v22
	v_fma_f32 v23, v2, v5, v23
	global_store_short_d16_hi v[14:15], v20, off offset:512
	global_store_short_d16_hi v[14:15], v21, off offset:640
	v_add_f32_e32 v4, v22, v140
	v_add_f32_e32 v5, v23, v141
	v_bfe_u32 v24, v4, 16, 1
	v_bfe_u32 v25, v5, 16, 1
	v_mul_f32_e32 v26, v0, v5
	v_mul_f32_e32 v27, v0, v4
	v_add3_u32 v24, v4, v24, s9
	v_add3_u32 v25, v5, v25, s9
	v_fma_f32 v26, v2, v4, -v26
	v_fma_f32 v27, v2, v5, v27
	global_store_short_d16_hi v[14:15], v24, off offset:768
	global_store_short_d16_hi v[14:15], v25, off offset:896
	v_add_f32_e32 v4, v26, v142
	v_add_f32_e32 v5, v27, v143
	v_bfe_u32 v20, v4, 16, 1
	v_bfe_u32 v21, v5, 16, 1
	v_mul_f32_e32 v22, v0, v5
	v_mul_f32_e32 v23, v0, v4
	v_add3_u32 v20, v4, v20, s9
	v_add3_u32 v21, v5, v21, s9
	v_fma_f32 v22, v2, v4, -v22
	v_fma_f32 v23, v2, v5, v23
	global_store_short_d16_hi v[14:15], v20, off offset:1024
	global_store_short_d16_hi v[14:15], v21, off offset:1152
	v_add_f32_e32 v4, v22, v144
	v_add_f32_e32 v5, v23, v145
	v_bfe_u32 v24, v4, 16, 1
	v_bfe_u32 v25, v5, 16, 1
	v_mul_f32_e32 v26, v0, v5
	v_mul_f32_e32 v27, v0, v4
	v_add3_u32 v24, v4, v24, s9
	v_add3_u32 v25, v5, v25, s9
	v_fma_f32 v26, v2, v4, -v26
	v_fma_f32 v27, v2, v5, v27
	global_store_short_d16_hi v[14:15], v24, off offset:1280
	global_store_short_d16_hi v[14:15], v25, off offset:1408
	v_add_f32_e32 v4, v26, v146
	v_add_f32_e32 v5, v27, v147
	v_bfe_u32 v20, v4, 16, 1
	v_bfe_u32 v21, v5, 16, 1
	v_mul_f32_e32 v22, v0, v5
	v_mul_f32_e32 v23, v0, v4
	v_add3_u32 v20, v4, v20, s9
	v_add3_u32 v21, v5, v21, s9
	v_fma_f32 v22, v2, v4, -v22
	v_fma_f32 v23, v2, v5, v23
	global_store_short_d16_hi v[14:15], v20, off offset:1536
	global_store_short_d16_hi v[14:15], v21, off offset:1664
	v_add_f32_e32 v4, v22, v148
	v_add_f32_e32 v5, v23, v149
	v_bfe_u32 v24, v4, 16, 1
	v_bfe_u32 v25, v5, 16, 1
	v_mul_f32_e32 v26, v0, v5
	v_mul_f32_e32 v27, v0, v4
	v_add3_u32 v24, v4, v24, s9
	v_add3_u32 v25, v5, v25, s9
	v_fma_f32 v26, v2, v4, -v26
	v_fma_f32 v27, v2, v5, v27
	global_store_short_d16_hi v[14:15], v24, off offset:1792
	global_store_short_d16_hi v[14:15], v25, off offset:1920
	v_add_f32_e32 v4, v26, v150
	v_add_f32_e32 v5, v27, v151
	v_lshl_add_u64 v[14:15], v[14:15], 0, s[2:3]
	v_bfe_u32 v20, v4, 16, 1
	v_bfe_u32 v21, v5, 16, 1
	v_mul_f32_e32 v22, v0, v5
	v_mul_f32_e32 v23, v0, v4
	v_add3_u32 v20, v4, v20, s9
	v_add3_u32 v21, v5, v21, s9
	v_fma_f32 v22, v2, v4, -v22
	v_fma_f32 v23, v2, v5, v23
	global_store_short_d16_hi v[14:15], v20, off offset:-2048
	global_store_short_d16_hi v[14:15], v21, off offset:-1920
	v_add_f32_e32 v4, v22, v152
	v_add_f32_e32 v5, v23, v153
	v_bfe_u32 v24, v4, 16, 1
	v_bfe_u32 v25, v5, 16, 1
	v_mul_f32_e32 v26, v0, v5
	v_mul_f32_e32 v27, v0, v4
	v_add3_u32 v24, v4, v24, s9
	v_add3_u32 v25, v5, v25, s9
	v_fma_f32 v26, v2, v4, -v26
	v_fma_f32 v27, v2, v5, v27
	global_store_short_d16_hi v[14:15], v24, off offset:-1792
	global_store_short_d16_hi v[14:15], v25, off offset:-1664
	v_add_f32_e32 v4, v26, v154
	v_add_f32_e32 v5, v27, v155
	v_bfe_u32 v20, v4, 16, 1
	v_bfe_u32 v21, v5, 16, 1
	v_mul_f32_e32 v22, v0, v5
	v_mul_f32_e32 v23, v0, v4
	v_add3_u32 v20, v4, v20, s9
	v_add3_u32 v21, v5, v21, s9
	v_fma_f32 v22, v2, v4, -v22
	v_fma_f32 v23, v2, v5, v23
	global_store_short_d16_hi v[14:15], v20, off offset:-1536
	global_store_short_d16_hi v[14:15], v21, off offset:-1408
	v_add_f32_e32 v4, v22, v156
	v_add_f32_e32 v5, v23, v157
	v_bfe_u32 v24, v4, 16, 1
	v_bfe_u32 v25, v5, 16, 1
	v_mul_f32_e32 v26, v0, v5
	v_mul_f32_e32 v27, v0, v4
	v_add3_u32 v24, v4, v24, s9
	v_add3_u32 v25, v5, v25, s9
	v_fma_f32 v26, v2, v4, -v26
; #define LBAR() do { asm volatile("s_waitcnt lgkmcnt(0)" ::: "memory"); __builtin_amdgcn_s_barrier(); asm volatile("" ::: "memory"); } while (0)
; #define S5_LOAD(SR, SI, cb) do { _Pragma("unroll") for (int i = 0; i < 16; ++i) { SR[i] = sc[(size_t)((cb) + i) * 128 + n]; SI[i] = sc[(size_t)((cb) + i) * 128 + 64 + n]; } } while (0)
; #define S5_ACC(SR, SI) do { _Pragma("unroll") for (int i = 0; i < 16; ++i) { const float nhr = atr * hr - ati * hi + SR[i], nhi = atr * hi + ati * hr + SI[i]; hr = nhr; hi = nhi; } } while (0)
; #define S5_STEP(SR, SI, cb) do { _Pragma("unroll") for (int i = 0; i < 16; ++i) { \
;         hp[(size_t)((cb) + i) * 128 + n] = (bf16)f2bf(hr); hp[(size_t)((cb) + i) * 128 + 64 + n] = (bf16)f2bf(hi); \
;         const float nhr = atr * hr - ati * hi + SR[i], nhi = atr * hi + ati * hr + SI[i]; hr = nhr; hi = nhi; } } while (0)
; __device__ __forceinline__ void s5_scan_block(LAS unsigned char* lds, const Args& a, const float* __restrict__ SC, bf16* HP, int g, int wave, int lane) {
;     ...
;     float hr = 0.f, hi = 0.f;
;     for (int cb = 0; cb < 64; cb += 16) { S5_LOAD(sr0, si0, cb); S5_ACC(sr0, si0); }
;     LBAR();
;     ex[wave * 128 + n] = hr; ex[wave * 128 + 64 + n] = hi;
;     LBAR();
;     hr = 0.f; hi = 0.f;
;     for (int w = 0; w < wave; ++w) { const float er = ex[w * 128 + n], ei = ex[w * 128 + 64 + n]; const float nhr = asr * hr - asi * hi + er, nhi = asr * hi + asi * hr + ei; hr = nhr; hi = nhi; }
;     for (int cb = 0; cb < 64; cb += 16) { S5_LOAD(sr0, si0, cb); S5_STEP(sr0, si0, cb); }
; __global__ void __launch_bounds__(512, 2) mega(Args a) {
;     ...
;                 asm volatile("s_waitcnt vmcnt(0)" ::: "memory");
;                 __syncthreads();
;                 if (tid == 0) { __builtin_amdgcn_fence(__ATOMIC_RELEASE, "agent"); asm volatile("s_waitcnt vmcnt(0)" ::: "memory"); __hip_atomic_store(flg + 64 * b, 1u, __ATOMIC_RELAXED, __HIP_MEMORY_SCOPE_AGENT); }
	v_fma_f32 v27, v2, v5, v27
	global_store_short_d16_hi v[14:15], v24, off offset:-1280
	global_store_short_d16_hi v[14:15], v25, off offset:-1152
	v_add_f32_e32 v4, v26, v158
	v_add_f32_e32 v5, v27, v159
	v_bfe_u32 v20, v4, 16, 1
	v_bfe_u32 v21, v5, 16, 1
	v_mul_f32_e32 v22, v0, v5
	v_mul_f32_e32 v23, v0, v4
	v_add3_u32 v20, v4, v20, s9
	v_add3_u32 v21, v5, v21, s9
	v_fma_f32 v22, v2, v4, -v22
	v_fma_f32 v23, v2, v5, v23
	global_store_short_d16_hi v[14:15], v20, off offset:-1024
	global_store_short_d16_hi v[14:15], v21, off offset:-896
	v_add_f32_e32 v4, v22, v160
	v_add_f32_e32 v5, v23, v161
	v_bfe_u32 v24, v4, 16, 1
	v_bfe_u32 v25, v5, 16, 1
	v_mul_f32_e32 v26, v0, v5
	v_mul_f32_e32 v27, v0, v4
	v_add3_u32 v24, v4, v24, s9
	v_add3_u32 v25, v5, v25, s9
	v_fma_f32 v26, v2, v4, -v26
	v_fma_f32 v27, v2, v5, v27
	global_store_short_d16_hi v[14:15], v24, off offset:-768
	global_store_short_d16_hi v[14:15], v25, off offset:-640
	v_add_f32_e32 v4, v26, v162
	v_add_f32_e32 v5, v27, v163
	v_bfe_u32 v20, v4, 16, 1
	v_bfe_u32 v21, v5, 16, 1
	v_mul_f32_e32 v22, v0, v5
	v_mul_f32_e32 v23, v0, v4
	v_add3_u32 v20, v4, v20, s9
	v_add3_u32 v21, v5, v21, s9
	v_fma_f32 v22, v2, v4, -v22
	v_fma_f32 v23, v2, v5, v23
	global_store_short_d16_hi v[14:15], v20, off offset:-512
	global_store_short_d16_hi v[14:15], v21, off offset:-384
	v_add_f32_e32 v4, v22, v164
	v_add_f32_e32 v5, v23, v165
	v_bfe_u32 v24, v4, 16, 1
	v_bfe_u32 v25, v5, 16, 1
	v_mul_f32_e32 v26, v0, v5
	v_mul_f32_e32 v27, v0, v4
	v_add3_u32 v24, v4, v24, s9
	v_add3_u32 v25, v5, v25, s9
	v_fma_f32 v26, v2, v4, -v26
	v_fma_f32 v27, v2, v5, v27
	global_store_short_d16_hi v[14:15], v24, off offset:-256
	global_store_short_d16_hi v[14:15], v25, off offset:-128
	v_add_f32_e32 v4, v26, v166
	v_add_f32_e32 v5, v27, v167
	v_bfe_u32 v20, v4, 16, 1
	v_bfe_u32 v21, v5, 16, 1
	v_mul_f32_e32 v22, v0, v5
	v_mul_f32_e32 v23, v0, v4
	v_add3_u32 v20, v4, v20, s9
	v_add3_u32 v21, v5, v21, s9
	v_fma_f32 v22, v2, v4, -v22
	v_fma_f32 v23, v2, v5, v23
	global_store_short_d16_hi v[14:15], v20, off
	global_store_short_d16_hi v[14:15], v21, off offset:128
	v_add_f32_e32 v4, v22, v168
	v_add_f32_e32 v5, v23, v169
	v_bfe_u32 v24, v4, 16, 1
	v_bfe_u32 v25, v5, 16, 1
	v_mul_f32_e32 v26, v0, v5
	v_mul_f32_e32 v27, v0, v4
	v_add3_u32 v24, v4, v24, s9
	v_add3_u32 v25, v5, v25, s9
	v_fma_f32 v26, v2, v4, -v26
	v_fma_f32 v27, v2, v5, v27
	global_store_short_d16_hi v[14:15], v24, off offset:256
	global_store_short_d16_hi v[14:15], v25, off offset:384
	v_add_f32_e32 v4, v26, v170
	v_add_f32_e32 v5, v27, v171
	v_bfe_u32 v20, v4, 16, 1
	v_bfe_u32 v21, v5, 16, 1
	v_mul_f32_e32 v22, v0, v5
	v_mul_f32_e32 v23, v0, v4
	v_add3_u32 v20, v4, v20, s9
	v_add3_u32 v21, v5, v21, s9
	v_fma_f32 v22, v2, v4, -v22
	v_fma_f32 v23, v2, v5, v23
	global_store_short_d16_hi v[14:15], v20, off offset:512
	global_store_short_d16_hi v[14:15], v21, off offset:640
	v_add_f32_e32 v4, v22, v172
	v_add_f32_e32 v5, v23, v173
	v_bfe_u32 v24, v4, 16, 1
	v_bfe_u32 v25, v5, 16, 1
	v_mul_f32_e32 v26, v0, v5
	v_mul_f32_e32 v27, v0, v4
	v_add3_u32 v24, v4, v24, s9
	v_add3_u32 v25, v5, v25, s9
	v_fma_f32 v26, v2, v4, -v26
	v_fma_f32 v27, v2, v5, v27
	global_store_short_d16_hi v[14:15], v24, off offset:768
	global_store_short_d16_hi v[14:15], v25, off offset:896
	v_add_f32_e32 v4, v26, v174
	v_add_f32_e32 v5, v27, v175
	v_bfe_u32 v20, v4, 16, 1
	v_bfe_u32 v21, v5, 16, 1
	v_mul_f32_e32 v22, v0, v5
	v_mul_f32_e32 v23, v0, v4
	v_add3_u32 v20, v4, v20, s9
	v_add3_u32 v21, v5, v21, s9
	v_fma_f32 v22, v2, v4, -v22
	v_fma_f32 v23, v2, v5, v23
	global_store_short_d16_hi v[14:15], v20, off offset:1024
	global_store_short_d16_hi v[14:15], v21, off offset:1152
	v_add_f32_e32 v4, v22, v176
	v_add_f32_e32 v5, v23, v177
	v_bfe_u32 v24, v4, 16, 1
	v_bfe_u32 v25, v5, 16, 1
	v_mul_f32_e32 v26, v0, v5
	v_mul_f32_e32 v27, v0, v4
	v_add3_u32 v24, v4, v24, s9
	v_add3_u32 v25, v5, v25, s9
	v_fma_f32 v26, v2, v4, -v26
	v_fma_f32 v27, v2, v5, v27
	global_store_short_d16_hi v[14:15], v24, off offset:1280
	global_store_short_d16_hi v[14:15], v25, off offset:1408
	v_add_f32_e32 v4, v26, v178
	v_add_f32_e32 v5, v27, v179
	v_bfe_u32 v20, v4, 16, 1
	v_bfe_u32 v21, v5, 16, 1
	v_mul_f32_e32 v22, v0, v5
	v_mul_f32_e32 v23, v0, v4
	v_add3_u32 v20, v4, v20, s9
	v_add3_u32 v21, v5, v21, s9
	v_fma_f32 v22, v2, v4, -v22
	v_fma_f32 v23, v2, v5, v23
	global_store_short_d16_hi v[14:15], v20, off offset:1536
	global_store_short_d16_hi v[14:15], v21, off offset:1664
	v_add_f32_e32 v4, v22, v180
	v_add_f32_e32 v5, v23, v181
	v_bfe_u32 v24, v4, 16, 1
	v_bfe_u32 v25, v5, 16, 1
	v_mul_f32_e32 v26, v0, v5
	v_mul_f32_e32 v27, v0, v4
	v_add3_u32 v24, v4, v24, s9
	v_add3_u32 v25, v5, v25, s9
	v_fma_f32 v26, v2, v4, -v26
	v_fma_f32 v27, v2, v5, v27
	global_store_short_d16_hi v[14:15], v24, off offset:1792
	global_store_short_d16_hi v[14:15], v25, off offset:1920
	v_add_f32_e32 v4, v26, v182
	v_add_f32_e32 v5, v27, v183
	s_waitcnt vmcnt(0)
	s_waitcnt lgkmcnt(0)
	s_barrier
	s_mov_b64 s[0:1], exec
	v_readlane_b32 s2, v245, 5
	v_readlane_b32 s3, v245, 6
	s_and_b64 s[2:3], s[0:1], s[2:3]
	s_mov_b64 exec, s[2:3]
	s_cbranch_execz .LBB0_781
	s_ashr_i32 s9, s8, 31
	s_lshl_b64 s[2:3], s[8:9], 2
	buffer_wbl2 sc1
	s_waitcnt vmcnt(0)
	s_waitcnt vmcnt(0)
	s_add_u32 s2, s24, s2
	s_addc_u32 s3, s25, s3
	v_mov_b32_e32 v0, 0
	v_mov_b32_e32 v1, 1
	global_store_dword v0, v1, s[2:3] sc1

; __device__ __forceinline__ float bflo(unsigned w) { return __uint_as_float(w << 16); }
; __device__ __forceinline__ float bfhi(unsigned w) { return __uint_as_float(w & 0xffff0000u); }
; __device__ __forceinline__ bf16* po_base(unsigned char* ws, int pat) { return (bf16*)(ws + (pat < 2 ? 436 * MiB + (size_t)pat * 32 * MiB : WS_Y)); }
; __device__ __forceinline__ void attn_combine(unsigned char* ws, const float* __restrict__ PM, bf16* CAT, int gtid, int gthreads, int iend = S * 128) {
;     for (int idx = gtid; idx < iend; idx += gthreads) {
;         const int t = idx >> 7, c = (idx & 127) * 8, hh = c >> 7;
;         float mm[3], ll[3];
; #pragma unroll
;         for (int p = 0; p < 3; ++p) { const f32x2_t ml = *(const f32x2_t*)(PM + (((size_t)p * S + t) * 8 + hh) * 2); mm[p] = ml[0]; ll[p] = ml[1]; }
;         const float ma = fmaxf(mm[0], fmaxf(mm[1], mm[2]));
;         float w[3], den = 0.f;
; #pragma unroll
;         for (int p = 0; p < 3; ++p) { w[p] = exp2f(mm[p] - ma) * ll[p]; den += w[p]; }
;         const float inv = 1.f / den;
;         float o[8] = {0.f, 0.f, 0.f, 0.f, 0.f, 0.f, 0.f, 0.f};
; #pragma unroll
;         for (int p = 0; p < 3; ++p) {
;             const u32x4 v = *(const u32x4*)(po_base(ws, p) + (size_t)t * 1024 + c); const float wp = w[p] * inv;
;             o[0] += wp * bflo(v.x); o[1] += wp * bfhi(v.x); o[2] += wp * bflo(v.y); o[3] += wp * bfhi(v.y); o[4] += wp * bflo(v.z); o[5] += wp * bfhi(v.z); o[6] += wp * bflo(v.w); o[7] += wp * bfhi(v.w);
; __global__ void __launch_bounds__(512, 2) mega(Args a) {
;     ...
;             const long NIT = (long)S * 128, W = 192 * 5 + 64 * 3;
;             const long c0 = b <= NG ? 3L * b : 192L + 5L * (b - NG), c1 = (b + 1) <= NG ? 3L * (b + 1) : 192L + 5L * (b + 1 - NG);
;             const int i0 = (int)(NIT * c0 / W), i1 = (int)(NIT * c1 / W);
;             attn_combine(ws, PM, CAT, i0 + tid, 512, i1);
.LBB0_790:
	s_lshl_b64 s[4:5], s[0:1], 21
	s_lshr_b64 s[0:1], s[0:1], 11
	s_mul_hi_u32 s6, s4, 0xe38e38e
	s_mul_i32 s7, s4, 0xe38e38e
	s_mul_i32 s8, s0, 0x38e38e39
	s_mul_hi_u32 s4, s4, 0x38e38e39
	s_mul_hi_u32 s1, s0, 0x38e38e39
	s_add_u32 s4, s8, s4
	s_addc_u32 s1, s1, 0
	s_add_u32 s4, s7, s4
	s_addc_u32 s4, s6, 0
	s_add_u32 s1, s1, s4
	s_addc_u32 s4, 0, 0
	s_mul_hi_u32 s6, s0, 0xe38e38e
	s_mul_i32 s0, s0, 0xe38e38e
	s_add_u32 s0, s0, s1
	s_addc_u32 s1, s6, s4
	s_ashr_i32 s4, s5, 31
	s_mul_i32 s5, s4, 0xe38e38e
	s_mul_hi_u32 s6, s4, 0x38e38e39
	s_add_i32 s5, s6, s5
	s_mul_i32 s4, s4, 0x38e38e39
	s_add_i32 s5, s5, s4
	s_add_u32 s0, s0, s4
	s_addc_u32 s1, s1, s5
	s_lshr_b32 s4, s1, 31
	s_lshr_b64 s[0:1], s[0:1], 6
	s_add_i32 s4, s0, s4
	s_lshl_b64 s[0:1], s[2:3], 21
	s_lshr_b64 s[2:3], s[2:3], 11
	s_mul_hi_u32 s5, s0, 0xe38e38e
	s_mul_i32 s6, s0, 0xe38e38e
	s_mul_i32 s7, s2, 0x38e38e39
	s_mul_hi_u32 s0, s0, 0x38e38e39
	s_mul_hi_u32 s3, s2, 0x38e38e39
	s_add_u32 s0, s7, s0
	s_addc_u32 s3, s3, 0
	s_add_u32 s0, s6, s0
	s_addc_u32 s0, s5, 0
	s_add_u32 s0, s3, s0
	s_addc_u32 s3, 0, 0
	s_mul_hi_u32 s5, s2, 0xe38e38e
	s_mul_i32 s2, s2, 0xe38e38e
	s_add_u32 s0, s2, s0
	s_addc_u32 s2, s5, s3
	s_ashr_i32 s1, s1, 31
	s_mul_i32 s3, s1, 0xe38e38e
	s_mul_hi_u32 s5, s1, 0x38e38e39
	s_add_i32 s3, s5, s3
	s_mul_i32 s1, s1, 0x38e38e39
	s_add_i32 s3, s3, s1
	s_add_u32 s0, s0, s1
	s_addc_u32 s1, s2, s3
	s_lshr_b32 s2, s1, 31
	s_lshr_b64 s[0:1], s[0:1], 6
	s_add_i32 s18, s0, s2
	s_mov_b64 s[2:3], exec
	s_sub_i32 s0, s66, 64
	s_cmp_lt_i32 s0, 0
	s_cbranch_scc1 .Lcmb_skip
	s_lshl_b32 s4, s0, 15
	s_add_i32 s18, s4, 0x8000
	s_mul_hi_u32 s4, s4, 0xaaaaaaab
	s_lshr_b32 s4, s4, 1
	s_mul_hi_u32 s18, s18, 0xaaaaaaab
	s_lshr_b32 s18, s18, 1
	v_add_u32_e32 v2, s4, v186
	v_readlane_b32 s26, v245, 38
	v_readlane_b32 s27, v245, 39
	s_add_u32 s6, s88, 0x600000
	s_addc_u32 s7, s89, 0
	s_add_u32 s8, s88, 0x700000
	s_addc_u32 s9, s89, 0
	s_add_u32 s16, s88, 0x1b400000
	s_addc_u32 s17, s89, 0
	s_add_u32 s20, s88, 0x1d400000
	s_addc_u32 s21, s89, 0
	v_readlane_b32 s22, v245, 15
	v_readlane_b32 s23, v245, 16
	s_sub_i32 s0, s18, s4
	s_add_i32 s0, s0, 2047
	s_lshr_b32 s0, s0, 11
	s_add_i32 s1, s18, -1
	s_mov_b32 s19, 0xc2fc0000
	v_mov_b32_e32 v1, 0
	v_mov_b32_e32 v4, 0x42800000
	v_not_b32_e32 v5, 63
.Lcmb_loop:
	v_min_i32_e32 v60, s1, v2
	v_ashrrev_i32_e32 v59, 7, v60
	v_lshrrev_b32_e32 v61, 1, v60
	v_and_b32_e32 v61, 56, v61
	v_lshl_or_b32 v61, v59, 6, v61
	global_load_dwordx2 v[40:41], v61, s[26:27]
	global_load_dwordx2 v[42:43], v61, s[6:7]
	global_load_dwordx2 v[44:45], v61, s[8:9]
	v_and_b32_e32 v58, 0x7f, v60
	v_lshlrev_b32_e32 v60, 4, v60
	v_lshlrev_b32_e32 v58, 4, v58
	global_load_dwordx4 v[46:49], v60, s[16:17]
	v_lshl_or_b32 v58, v59, 12, v58
	global_load_dwordx4 v[50:53], v60, s[20:21]
	global_load_dwordx4 v[54:57], v60, s[22:23]
	v_add_u32_e32 v84, 512, v2
	v_min_i32_e32 v84, s1, v84
	v_ashrrev_i32_e32 v83, 7, v84
	v_lshrrev_b32_e32 v85, 1, v84
	v_and_b32_e32 v85, 56, v85
	v_lshl_or_b32 v85, v83, 6, v85
	global_load_dwordx2 v[64:65], v85, s[26:27]
	global_load_dwordx2 v[66:67], v85, s[6:7]
	global_load_dwordx2 v[68:69], v85, s[8:9]
	v_and_b32_e32 v82, 0x7f, v84
	v_lshlrev_b32_e32 v84, 4, v84
	v_lshlrev_b32_e32 v82, 4, v82
	global_load_dwordx4 v[70:73], v84, s[16:17]
	v_lshl_or_b32 v82, v83, 12, v82
	global_load_dwordx4 v[74:77], v84, s[20:21]
	global_load_dwordx4 v[78:81], v84, s[22:23]
	v_add_u32_e32 v108, 1024, v2
	v_min_i32_e32 v108, s1, v108
	v_ashrrev_i32_e32 v107, 7, v108
	v_lshrrev_b32_e32 v109, 1, v108
	v_and_b32_e32 v109, 56, v109
	v_lshl_or_b32 v109, v107, 6, v109
	global_load_dwordx2 v[88:89], v109, s[26:27]
	global_load_dwordx2 v[90:91], v109, s[6:7]
	global_load_dwordx2 v[92:93], v109, s[8:9]
	v_and_b32_e32 v106, 0x7f, v108
	v_lshlrev_b32_e32 v108, 4, v108
	v_lshlrev_b32_e32 v106, 4, v106
	global_load_dwordx4 v[94:97], v108, s[16:17]
	v_lshl_or_b32 v106, v107, 12, v106
	global_load_dwordx4 v[98:101], v108, s[20:21]
	global_load_dwordx4 v[102:105], v108, s[22:23]
	v_add_u32_e32 v132, 1536, v2
	v_min_i32_e32 v132, s1, v132
	v_ashrrev_i32_e32 v131, 7, v132
	v_lshrrev_b32_e32 v133, 1, v132
	v_and_b32_e32 v133, 56, v133
	v_lshl_or_b32 v133, v131, 6, v133
	global_load_dwordx2 v[112:113], v133, s[26:27]
	global_load_dwordx2 v[114:115], v133, s[6:7]
	global_load_dwordx2 v[116:117], v133, s[8:9]
	v_and_b32_e32 v130, 0x7f, v132
	v_lshlrev_b32_e32 v132, 4, v132
	v_lshlrev_b32_e32 v130, 4, v130
	global_load_dwordx4 v[118:121], v132, s[16:17]
	v_lshl_or_b32 v130, v131, 12, v130
	global_load_dwordx4 v[122:125], v132, s[20:21]
	global_load_dwordx4 v[126:129], v132, s[22:23]
	v_add_u32_e32 v2, 2048, v2
	s_add_i32 s0, s0, -1
	s_waitcnt vmcnt(18)
; __device__ __forceinline__ unsigned pk2(float lo, float hi) { f32x2_t v = {lo, hi}; bf16x2_t b = __builtin_convertvector(v, bf16x2_t); return __builtin_bit_cast(unsigned, b); }
; __device__ __forceinline__ float bflo(unsigned w) { return __uint_as_float(w << 16); }
; __device__ __forceinline__ float bfhi(unsigned w) { return __uint_as_float(w & 0xffff0000u); }
; __device__ __forceinline__ bf16* po_base(unsigned char* ws, int pat) { return (bf16*)(ws + (pat < 2 ? 436 * MiB + (size_t)pat * 32 * MiB : WS_Y)); }
; __device__ __forceinline__ void attn_combine(unsigned char* ws, const float* __restrict__ PM, bf16* CAT, int gtid, int gthreads, int iend = S * 128) {
;     for (int idx = gtid; idx < iend; idx += gthreads) {
;         const int t = idx >> 7, c = (idx & 127) * 8, hh = c >> 7;
;         float mm[3], ll[3];
; #pragma unroll
;         for (int p = 0; p < 3; ++p) { const f32x2_t ml = *(const f32x2_t*)(PM + (((size_t)p * S + t) * 8 + hh) * 2); mm[p] = ml[0]; ll[p] = ml[1]; }
;         const float ma = fmaxf(mm[0], fmaxf(mm[1], mm[2]));
;         float w[3], den = 0.f;
; #pragma unroll
;         for (int p = 0; p < 3; ++p) { w[p] = exp2f(mm[p] - ma) * ll[p]; den += w[p]; }
;         const float inv = 1.f / den;
;         float o[8] = {0.f, 0.f, 0.f, 0.f, 0.f, 0.f, 0.f, 0.f};
; #pragma unroll
;         for (int p = 0; p < 3; ++p) {
;             const u32x4 v = *(const u32x4*)(po_base(ws, p) + (size_t)t * 1024 + c); const float wp = w[p] * inv;
;             o[0] += wp * bflo(v.x); o[1] += wp * bfhi(v.x); o[2] += wp * bflo(v.y); o[3] += wp * bfhi(v.y); o[4] += wp * bflo(v.z); o[5] += wp * bfhi(v.z); o[6] += wp * bflo(v.w); o[7] += wp * bfhi(v.w);
;         }
;         u32x4 ov; ov.x = pk2(o[0], o[1]); ov.y = pk2(o[2], o[3]); ov.z = pk2(o[4], o[5]); ov.w = pk2(o[6], o[7]);
;         *(u32x4*)(CAT + (size_t)t * 2048 + c) = ov;
	v_max3_f32 v0, v40, v42, v44
	v_sub_f32_e32 v18, v40, v0
	v_sub_f32_e32 v36, v42, v0
	v_sub_f32_e32 v0, v44, v0
	v_cmp_gt_f32_e32 vcc, s19, v18
	v_cmp_gt_f32_e64 s[4:5], s19, v36
	v_cmp_gt_f32_e64 s[32:33], s19, v0
	v_cndmask_b32_e32 v37, 0, v4, vcc
	v_cndmask_b32_e64 v38, 0, v4, s[4:5]
	v_cndmask_b32_e64 v39, 0, v4, s[32:33]
	v_add_f32_e32 v18, v18, v37
	v_add_f32_e32 v36, v36, v38
	v_add_f32_e32 v0, v0, v39
	v_exp_f32_e32 v18, v18
	v_exp_f32_e32 v36, v36
	v_exp_f32_e32 v0, v0
	v_cndmask_b32_e32 v37, 0, v5, vcc
	v_cndmask_b32_e64 v38, 0, v5, s[4:5]
	v_cndmask_b32_e64 v39, 0, v5, s[32:33]
	v_mov_b32_e32 v20, v45
	v_mov_b32_e32 v21, v43
	v_ldexp_f32 v18, v18, v37
	v_ldexp_f32 v37, v36, v38
	v_ldexp_f32 v36, v0, v39
	v_mul_f32_e32 v0, v41, v18
	v_fma_f32 v38, v41, v18, 0
	v_pk_mul_f32 v[18:19], v[20:21], v[36:37]
	v_add_f32_e32 v20, v19, v38
	v_add_f32_e32 v20, v18, v20
	v_div_scale_f32 v21, s[4:5], v20, v20, 1.0
	v_rcp_f32_e32 v37, v21
	v_div_scale_f32 v36, vcc, 1.0, v20, 1.0
	v_fma_f32 v38, -v21, v37, 1.0
	v_fmac_f32_e32 v37, v38, v37
	v_mul_f32_e32 v38, v36, v37
	v_fma_f32 v39, -v21, v38, v36
	v_fmac_f32_e32 v38, v39, v37
	v_fma_f32 v21, -v21, v38, v36
	v_div_fmas_f32 v21, v21, v37, v38
	v_div_fixup_f32 v21, v21, v20, 1.0
	v_mul_f32_e32 v0, v0, v21
	v_mul_f32_e32 v20, v19, v21
	v_mul_f32_e32 v18, v18, v21
	v_lshlrev_b32_e32 v22, 16, v46
	v_and_b32_e32 v23, 0xffff0000, v46
	v_lshlrev_b32_e32 v6, 16, v47
	v_and_b32_e32 v7, 0xffff0000, v47
	v_lshlrev_b32_e32 v30, 16, v48
	v_and_b32_e32 v31, 0xffff0000, v48
	v_lshlrev_b32_e32 v8, 16, v49
	v_and_b32_e32 v9, 0xffff0000, v49
	v_lshlrev_b32_e32 v26, 16, v50
	v_and_b32_e32 v27, 0xffff0000, v50
	v_lshlrev_b32_e32 v10, 16, v51
	v_and_b32_e32 v11, 0xffff0000, v51
	v_lshlrev_b32_e32 v32, 16, v52
	v_and_b32_e32 v33, 0xffff0000, v52
	v_lshlrev_b32_e32 v12, 16, v53
	v_and_b32_e32 v13, 0xffff0000, v53
	v_pk_fma_f32 v[22:23], v[0:1], v[22:23], 0 op_sel_hi:[0,1,0]
	v_pk_fma_f32 v[6:7], v[0:1], v[6:7], 0 op_sel_hi:[0,1,0]
	v_pk_fma_f32 v[30:31], v[0:1], v[30:31], 0 op_sel_hi:[0,1,0]
	v_pk_fma_f32 v[8:9], v[0:1], v[8:9], 0 op_sel_hi:[0,1,0]
	v_lshlrev_b32_e32 v28, 16, v54
	v_and_b32_e32 v29, 0xffff0000, v54
	v_lshlrev_b32_e32 v14, 16, v55
	v_and_b32_e32 v15, 0xffff0000, v55
	v_lshlrev_b32_e32 v34, 16, v56
	v_and_b32_e32 v35, 0xffff0000, v56
	v_lshlrev_b32_e32 v16, 16, v57
	v_and_b32_e32 v17, 0xffff0000, v57
	v_pk_fma_f32 v[22:23], v[20:21], v[26:27], v[22:23] op_sel_hi:[0,1,1]
	v_pk_fma_f32 v[6:7], v[20:21], v[10:11], v[6:7] op_sel_hi:[0,1,1]
	v_pk_fma_f32 v[10:11], v[20:21], v[32:33], v[30:31] op_sel_hi:[0,1,1]
	v_pk_fma_f32 v[8:9], v[20:21], v[12:13], v[8:9] op_sel_hi:[0,1,1]
	v_pk_fma_f32 v[12:13], v[18:19], v[28:29], v[22:23] op_sel_hi:[0,1,1]
	v_pk_fma_f32 v[14:15], v[18:19], v[14:15], v[6:7] op_sel_hi:[0,1,1]
	v_pk_fma_f32 v[10:11], v[18:19], v[34:35], v[10:11] op_sel_hi:[0,1,1]
	v_pk_fma_f32 v[16:17], v[18:19], v[16:17], v[8:9] op_sel_hi:[0,1,1]
	v_cvt_pk_bf16_f32 v46, v12, v13
	v_cvt_pk_bf16_f32 v47, v14, v15
	v_cvt_pk_bf16_f32 v48, v10, v11
	v_cvt_pk_bf16_f32 v49, v16, v17
	global_store_dwordx4 v58, v[46:49], s[10:11]
	s_waitcnt vmcnt(13)
	v_max3_f32 v0, v64, v66, v68
	v_sub_f32_e32 v18, v64, v0
	v_sub_f32_e32 v36, v66, v0
	v_sub_f32_e32 v0, v68, v0
	v_cmp_gt_f32_e32 vcc, s19, v18
	v_cmp_gt_f32_e64 s[4:5], s19, v36
	v_cmp_gt_f32_e64 s[32:33], s19, v0
	v_cndmask_b32_e32 v37, 0, v4, vcc
	v_cndmask_b32_e64 v38, 0, v4, s[4:5]
	v_cndmask_b32_e64 v39, 0, v4, s[32:33]
	v_add_f32_e32 v18, v18, v37
	v_add_f32_e32 v36, v36, v38
	v_add_f32_e32 v0, v0, v39
	v_exp_f32_e32 v18, v18
	v_exp_f32_e32 v36, v36
	v_exp_f32_e32 v0, v0
	v_cndmask_b32_e32 v37, 0, v5, vcc
	v_cndmask_b32_e64 v38, 0, v5, s[4:5]
	v_cndmask_b32_e64 v39, 0, v5, s[32:33]
	v_mov_b32_e32 v20, v69
	v_mov_b32_e32 v21, v67
	v_ldexp_f32 v18, v18, v37
	v_ldexp_f32 v37, v36, v38
	v_ldexp_f32 v36, v0, v39
	v_mul_f32_e32 v0, v65, v18
	v_fma_f32 v38, v65, v18, 0
	v_pk_mul_f32 v[18:19], v[20:21], v[36:37]
	v_add_f32_e32 v20, v19, v38
	v_add_f32_e32 v20, v18, v20
	v_div_scale_f32 v21, s[4:5], v20, v20, 1.0
	v_rcp_f32_e32 v37, v21
	v_div_scale_f32 v36, vcc, 1.0, v20, 1.0
	v_fma_f32 v38, -v21, v37, 1.0
	v_fmac_f32_e32 v37, v38, v37
	v_mul_f32_e32 v38, v36, v37
	v_fma_f32 v39, -v21, v38, v36
	v_fmac_f32_e32 v38, v39, v37
	v_fma_f32 v21, -v21, v38, v36
	v_div_fmas_f32 v21, v21, v37, v38
	v_div_fixup_f32 v21, v21, v20, 1.0
	v_mul_f32_e32 v0, v0, v21
	v_mul_f32_e32 v20, v19, v21
	v_mul_f32_e32 v18, v18, v21
	v_lshlrev_b32_e32 v22, 16, v70
	v_and_b32_e32 v23, 0xffff0000, v70
	v_lshlrev_b32_e32 v6, 16, v71
	v_and_b32_e32 v7, 0xffff0000, v71
	v_lshlrev_b32_e32 v30, 16, v72
	v_and_b32_e32 v31, 0xffff0000, v72
	v_lshlrev_b32_e32 v8, 16, v73
	v_and_b32_e32 v9, 0xffff0000, v73
	v_lshlrev_b32_e32 v26, 16, v74
	v_and_b32_e32 v27, 0xffff0000, v74
	v_lshlrev_b32_e32 v10, 16, v75
	v_and_b32_e32 v11, 0xffff0000, v75
	v_lshlrev_b32_e32 v32, 16, v76
	v_and_b32_e32 v33, 0xffff0000, v76
	v_lshlrev_b32_e32 v12, 16, v77
	v_and_b32_e32 v13, 0xffff0000, v77
	v_pk_fma_f32 v[22:23], v[0:1], v[22:23], 0 op_sel_hi:[0,1,0]
	v_pk_fma_f32 v[6:7], v[0:1], v[6:7], 0 op_sel_hi:[0,1,0]
	v_pk_fma_f32 v[30:31], v[0:1], v[30:31], 0 op_sel_hi:[0,1,0]
	v_pk_fma_f32 v[8:9], v[0:1], v[8:9], 0 op_sel_hi:[0,1,0]
	v_lshlrev_b32_e32 v28, 16, v78
	v_and_b32_e32 v29, 0xffff0000, v78
	v_lshlrev_b32_e32 v14, 16, v79
	v_and_b32_e32 v15, 0xffff0000, v79
	v_lshlrev_b32_e32 v34, 16, v80
	v_and_b32_e32 v35, 0xffff0000, v80
	v_lshlrev_b32_e32 v16, 16, v81
	v_and_b32_e32 v17, 0xffff0000, v81
	v_pk_fma_f32 v[22:23], v[20:21], v[26:27], v[22:23] op_sel_hi:[0,1,1]
	v_pk_fma_f32 v[6:7], v[20:21], v[10:11], v[6:7] op_sel_hi:[0,1,1]
	v_pk_fma_f32 v[10:11], v[20:21], v[32:33], v[30:31] op_sel_hi:[0,1,1]
	v_pk_fma_f32 v[8:9], v[20:21], v[12:13], v[8:9] op_sel_hi:[0,1,1]
	v_pk_fma_f32 v[12:13], v[18:19], v[28:29], v[22:23] op_sel_hi:[0,1,1]
	v_pk_fma_f32 v[14:15], v[18:19], v[14:15], v[6:7] op_sel_hi:[0,1,1]
	v_pk_fma_f32 v[10:11], v[18:19], v[34:35], v[10:11] op_sel_hi:[0,1,1]
	v_pk_fma_f32 v[16:17], v[18:19], v[16:17], v[8:9] op_sel_hi:[0,1,1]
	v_cvt_pk_bf16_f32 v70, v12, v13
	v_cvt_pk_bf16_f32 v71, v14, v15
	v_cvt_pk_bf16_f32 v72, v10, v11
	v_cvt_pk_bf16_f32 v73, v16, v17
	global_store_dwordx4 v82, v[70:73], s[10:11]
	s_waitcnt vmcnt(8)
; __device__ __forceinline__ unsigned pk2(float lo, float hi) { f32x2_t v = {lo, hi}; bf16x2_t b = __builtin_convertvector(v, bf16x2_t); return __builtin_bit_cast(unsigned, b); }
; __device__ __forceinline__ float bflo(unsigned w) { return __uint_as_float(w << 16); }
; __device__ __forceinline__ float bfhi(unsigned w) { return __uint_as_float(w & 0xffff0000u); }
; __device__ __forceinline__ bf16* po_base(unsigned char* ws, int pat) { return (bf16*)(ws + (pat < 2 ? 436 * MiB + (size_t)pat * 32 * MiB : WS_Y)); }
; __device__ __forceinline__ void attn_combine(unsigned char* ws, const float* __restrict__ PM, bf16* CAT, int gtid, int gthreads, int iend = S * 128) {
;     for (int idx = gtid; idx < iend; idx += gthreads) {
;         const int t = idx >> 7, c = (idx & 127) * 8, hh = c >> 7;
;         float mm[3], ll[3];
; #pragma unroll
;         for (int p = 0; p < 3; ++p) { const f32x2_t ml = *(const f32x2_t*)(PM + (((size_t)p * S + t) * 8 + hh) * 2); mm[p] = ml[0]; ll[p] = ml[1]; }
;         const float ma = fmaxf(mm[0], fmaxf(mm[1], mm[2]));
;         float w[3], den = 0.f;
; #pragma unroll
;         for (int p = 0; p < 3; ++p) { w[p] = exp2f(mm[p] - ma) * ll[p]; den += w[p]; }
;         const float inv = 1.f / den;
;         float o[8] = {0.f, 0.f, 0.f, 0.f, 0.f, 0.f, 0.f, 0.f};
; #pragma unroll
;         for (int p = 0; p < 3; ++p) {
;             const u32x4 v = *(const u32x4*)(po_base(ws, p) + (size_t)t * 1024 + c); const float wp = w[p] * inv;
;             o[0] += wp * bflo(v.x); o[1] += wp * bfhi(v.x); o[2] += wp * bflo(v.y); o[3] += wp * bfhi(v.y); o[4] += wp * bflo(v.z); o[5] += wp * bfhi(v.z); o[6] += wp * bflo(v.w); o[7] += wp * bfhi(v.w);
;         }
;         u32x4 ov; ov.x = pk2(o[0], o[1]); ov.y = pk2(o[2], o[3]); ov.z = pk2(o[4], o[5]); ov.w = pk2(o[6], o[7]);
;         *(u32x4*)(CAT + (size_t)t * 2048 + c) = ov;
; __global__ void __launch_bounds__(512, 2) mega(Args a) {
;     ...
;             const int g = b >> 2;
;             if (tid == 0) { unsigned sp = 0; while (__hip_atomic_load(flg + 64 * g, __ATOMIC_RELAXED, __HIP_MEMORY_SCOPE_AGENT) == 0u) { __builtin_amdgcn_s_sleep(4); if (++sp > (1u << 22)) break; }
;                 __builtin_amdgcn_fence(__ATOMIC_ACQUIRE, "agent"); asm volatile("s_waitcnt vmcnt(0)" ::: "memory"); }
	v_max3_f32 v0, v88, v90, v92
	v_sub_f32_e32 v18, v88, v0
	v_sub_f32_e32 v36, v90, v0
	v_sub_f32_e32 v0, v92, v0
	v_cmp_gt_f32_e32 vcc, s19, v18
	v_cmp_gt_f32_e64 s[4:5], s19, v36
	v_cmp_gt_f32_e64 s[32:33], s19, v0
	v_cndmask_b32_e32 v37, 0, v4, vcc
	v_cndmask_b32_e64 v38, 0, v4, s[4:5]
	v_cndmask_b32_e64 v39, 0, v4, s[32:33]
	v_add_f32_e32 v18, v18, v37
	v_add_f32_e32 v36, v36, v38
	v_add_f32_e32 v0, v0, v39
	v_exp_f32_e32 v18, v18
	v_exp_f32_e32 v36, v36
	v_exp_f32_e32 v0, v0
	v_cndmask_b32_e32 v37, 0, v5, vcc
	v_cndmask_b32_e64 v38, 0, v5, s[4:5]
	v_cndmask_b32_e64 v39, 0, v5, s[32:33]
	v_mov_b32_e32 v20, v93
	v_mov_b32_e32 v21, v91
	v_ldexp_f32 v18, v18, v37
	v_ldexp_f32 v37, v36, v38
	v_ldexp_f32 v36, v0, v39
	v_mul_f32_e32 v0, v89, v18
	v_fma_f32 v38, v89, v18, 0
	v_pk_mul_f32 v[18:19], v[20:21], v[36:37]
	v_add_f32_e32 v20, v19, v38
	v_add_f32_e32 v20, v18, v20
	v_div_scale_f32 v21, s[4:5], v20, v20, 1.0
	v_rcp_f32_e32 v37, v21
	v_div_scale_f32 v36, vcc, 1.0, v20, 1.0
	v_fma_f32 v38, -v21, v37, 1.0
	v_fmac_f32_e32 v37, v38, v37
	v_mul_f32_e32 v38, v36, v37
	v_fma_f32 v39, -v21, v38, v36
	v_fmac_f32_e32 v38, v39, v37
	v_fma_f32 v21, -v21, v38, v36
	v_div_fmas_f32 v21, v21, v37, v38
	v_div_fixup_f32 v21, v21, v20, 1.0
	v_mul_f32_e32 v0, v0, v21
	v_mul_f32_e32 v20, v19, v21
	v_mul_f32_e32 v18, v18, v21
	v_lshlrev_b32_e32 v22, 16, v94
	v_and_b32_e32 v23, 0xffff0000, v94
	v_lshlrev_b32_e32 v6, 16, v95
	v_and_b32_e32 v7, 0xffff0000, v95
	v_lshlrev_b32_e32 v30, 16, v96
	v_and_b32_e32 v31, 0xffff0000, v96
	v_lshlrev_b32_e32 v8, 16, v97
	v_and_b32_e32 v9, 0xffff0000, v97
	v_lshlrev_b32_e32 v26, 16, v98
	v_and_b32_e32 v27, 0xffff0000, v98
	v_lshlrev_b32_e32 v10, 16, v99
	v_and_b32_e32 v11, 0xffff0000, v99
	v_lshlrev_b32_e32 v32, 16, v100
	v_and_b32_e32 v33, 0xffff0000, v100
	v_lshlrev_b32_e32 v12, 16, v101
	v_and_b32_e32 v13, 0xffff0000, v101
	v_pk_fma_f32 v[22:23], v[0:1], v[22:23], 0 op_sel_hi:[0,1,0]
	v_pk_fma_f32 v[6:7], v[0:1], v[6:7], 0 op_sel_hi:[0,1,0]
	v_pk_fma_f32 v[30:31], v[0:1], v[30:31], 0 op_sel_hi:[0,1,0]
	v_pk_fma_f32 v[8:9], v[0:1], v[8:9], 0 op_sel_hi:[0,1,0]
	v_lshlrev_b32_e32 v28, 16, v102
	v_and_b32_e32 v29, 0xffff0000, v102
	v_lshlrev_b32_e32 v14, 16, v103
	v_and_b32_e32 v15, 0xffff0000, v103
	v_lshlrev_b32_e32 v34, 16, v104
	v_and_b32_e32 v35, 0xffff0000, v104
	v_lshlrev_b32_e32 v16, 16, v105
	v_and_b32_e32 v17, 0xffff0000, v105
	v_pk_fma_f32 v[22:23], v[20:21], v[26:27], v[22:23] op_sel_hi:[0,1,1]
	v_pk_fma_f32 v[6:7], v[20:21], v[10:11], v[6:7] op_sel_hi:[0,1,1]
	v_pk_fma_f32 v[10:11], v[20:21], v[32:33], v[30:31] op_sel_hi:[0,1,1]
	v_pk_fma_f32 v[8:9], v[20:21], v[12:13], v[8:9] op_sel_hi:[0,1,1]
	v_pk_fma_f32 v[12:13], v[18:19], v[28:29], v[22:23] op_sel_hi:[0,1,1]
	v_pk_fma_f32 v[14:15], v[18:19], v[14:15], v[6:7] op_sel_hi:[0,1,1]
	v_pk_fma_f32 v[10:11], v[18:19], v[34:35], v[10:11] op_sel_hi:[0,1,1]
	v_pk_fma_f32 v[16:17], v[18:19], v[16:17], v[8:9] op_sel_hi:[0,1,1]
	v_cvt_pk_bf16_f32 v94, v12, v13
	v_cvt_pk_bf16_f32 v95, v14, v15
	v_cvt_pk_bf16_f32 v96, v10, v11
	v_cvt_pk_bf16_f32 v97, v16, v17
	global_store_dwordx4 v106, v[94:97], s[10:11]
	s_waitcnt vmcnt(3)
	v_max3_f32 v0, v112, v114, v116
	v_sub_f32_e32 v18, v112, v0
	v_sub_f32_e32 v36, v114, v0
	v_sub_f32_e32 v0, v116, v0
	v_cmp_gt_f32_e32 vcc, s19, v18
	v_cmp_gt_f32_e64 s[4:5], s19, v36
	v_cmp_gt_f32_e64 s[32:33], s19, v0
	v_cndmask_b32_e32 v37, 0, v4, vcc
	v_cndmask_b32_e64 v38, 0, v4, s[4:5]
	v_cndmask_b32_e64 v39, 0, v4, s[32:33]
	v_add_f32_e32 v18, v18, v37
	v_add_f32_e32 v36, v36, v38
	v_add_f32_e32 v0, v0, v39
	v_exp_f32_e32 v18, v18
	v_exp_f32_e32 v36, v36
	v_exp_f32_e32 v0, v0
	v_cndmask_b32_e32 v37, 0, v5, vcc
	v_cndmask_b32_e64 v38, 0, v5, s[4:5]
	v_cndmask_b32_e64 v39, 0, v5, s[32:33]
	v_mov_b32_e32 v20, v117
	v_mov_b32_e32 v21, v115
	v_ldexp_f32 v18, v18, v37
	v_ldexp_f32 v37, v36, v38
	v_ldexp_f32 v36, v0, v39
	v_mul_f32_e32 v0, v113, v18
	v_fma_f32 v38, v113, v18, 0
	v_pk_mul_f32 v[18:19], v[20:21], v[36:37]
	v_add_f32_e32 v20, v19, v38
	v_add_f32_e32 v20, v18, v20
	v_div_scale_f32 v21, s[4:5], v20, v20, 1.0
	v_rcp_f32_e32 v37, v21
	v_div_scale_f32 v36, vcc, 1.0, v20, 1.0
	v_fma_f32 v38, -v21, v37, 1.0
	v_fmac_f32_e32 v37, v38, v37
	v_mul_f32_e32 v38, v36, v37
	v_fma_f32 v39, -v21, v38, v36
	v_fmac_f32_e32 v38, v39, v37
	v_fma_f32 v21, -v21, v38, v36
	v_div_fmas_f32 v21, v21, v37, v38
	v_div_fixup_f32 v21, v21, v20, 1.0
	v_mul_f32_e32 v0, v0, v21
	v_mul_f32_e32 v20, v19, v21
	v_mul_f32_e32 v18, v18, v21
	v_lshlrev_b32_e32 v22, 16, v118
	v_and_b32_e32 v23, 0xffff0000, v118
	v_lshlrev_b32_e32 v6, 16, v119
	v_and_b32_e32 v7, 0xffff0000, v119
	v_lshlrev_b32_e32 v30, 16, v120
	v_and_b32_e32 v31, 0xffff0000, v120
	v_lshlrev_b32_e32 v8, 16, v121
	v_and_b32_e32 v9, 0xffff0000, v121
	v_lshlrev_b32_e32 v26, 16, v122
	v_and_b32_e32 v27, 0xffff0000, v122
	v_lshlrev_b32_e32 v10, 16, v123
	v_and_b32_e32 v11, 0xffff0000, v123
	v_lshlrev_b32_e32 v32, 16, v124
	v_and_b32_e32 v33, 0xffff0000, v124
	v_lshlrev_b32_e32 v12, 16, v125
	v_and_b32_e32 v13, 0xffff0000, v125
	v_pk_fma_f32 v[22:23], v[0:1], v[22:23], 0 op_sel_hi:[0,1,0]
	v_pk_fma_f32 v[6:7], v[0:1], v[6:7], 0 op_sel_hi:[0,1,0]
	v_pk_fma_f32 v[30:31], v[0:1], v[30:31], 0 op_sel_hi:[0,1,0]
	v_pk_fma_f32 v[8:9], v[0:1], v[8:9], 0 op_sel_hi:[0,1,0]
	v_lshlrev_b32_e32 v28, 16, v126
	v_and_b32_e32 v29, 0xffff0000, v126
	v_lshlrev_b32_e32 v14, 16, v127
	v_and_b32_e32 v15, 0xffff0000, v127
	v_lshlrev_b32_e32 v34, 16, v128
	v_and_b32_e32 v35, 0xffff0000, v128
	v_lshlrev_b32_e32 v16, 16, v129
	v_and_b32_e32 v17, 0xffff0000, v129
	v_pk_fma_f32 v[22:23], v[20:21], v[26:27], v[22:23] op_sel_hi:[0,1,1]
	v_pk_fma_f32 v[6:7], v[20:21], v[10:11], v[6:7] op_sel_hi:[0,1,1]
	v_pk_fma_f32 v[10:11], v[20:21], v[32:33], v[30:31] op_sel_hi:[0,1,1]
	v_pk_fma_f32 v[8:9], v[20:21], v[12:13], v[8:9] op_sel_hi:[0,1,1]
	v_pk_fma_f32 v[12:13], v[18:19], v[28:29], v[22:23] op_sel_hi:[0,1,1]
	v_pk_fma_f32 v[14:15], v[18:19], v[14:15], v[6:7] op_sel_hi:[0,1,1]
	v_pk_fma_f32 v[10:11], v[18:19], v[34:35], v[10:11] op_sel_hi:[0,1,1]
	v_pk_fma_f32 v[16:17], v[18:19], v[16:17], v[8:9] op_sel_hi:[0,1,1]
	v_cvt_pk_bf16_f32 v118, v12, v13
	v_cvt_pk_bf16_f32 v119, v14, v15
	v_cvt_pk_bf16_f32 v120, v10, v11
	v_cvt_pk_bf16_f32 v121, v16, v17
	global_store_dwordx4 v130, v[118:121], s[10:11]
	s_cmp_lg_u32 s0, 0
	s_cbranch_scc1 .Lcmb_loop
.Lcmb_skip:
.LBB0_793:
	s_or_b64 exec, exec, s[2:3]
	s_mov_b64 s[0:1], exec
	v_readlane_b32 s2, v245, 5
	v_readlane_b32 s3, v245, 6
	s_and_b64 s[2:3], s[0:1], s[2:3]
	s_mov_b64 exec, s[2:3]
	s_cbranch_execz .LBB0_803
	s_lshl_b32 s2, s66, 4
	s_andn2_b32 s2, s2, 63
	s_ashr_i32 s3, s2, 31
	s_lshl_b64 s[2:3], s[2:3], 2
	s_add_u32 s2, s24, s2
	s_addc_u32 s3, s25, s3
	s_mov_b32 s6, 0x400001
	v_mov_b32_e32 v0, 0
	s_branch .LBB0_796

;     __device__ __forceinline__ bool next(int i, pg8::Unit& u) const { const long L = (long)i * G + c; if (L >= nwg) return false; const int xcd = (int)(L & 7), off = (int)(L >> 3); u.pm = xcd * 8 + (off >> 3); u.pn = off & 7; return true; }
;     __host__ __device__ bool next(int i, Unit& u) const {
;         const long L = (long)i * G + c; if (L >= nwg) return false;
;         int wgid = (int)L; { const int q = nwg / NXCD, r = nwg % NXCD, xcd = wgid % NXCD, off = wgid / NXCD; wgid = (xcd < r ? xcd * (q + 1) : r * (q + 1) + (xcd - r) * q) + off; }
;         const int nig = WGM * nN, gid = wgid / nig, fm = gid * WGM, gsz = (nM - fm) < WGM ? (nM - fm) : WGM;
;         u.pm = fm + ((wgid % nig) % gsz); u.pn = (wgid % nig) / gsz; return true;
;     __device__ __forceinline__ void operator()(const pg8::f32x4 (&acc)[2][2][4][2], const pg8::Unit& u, int wr, int wc, int fr, int fq) const {
;     ...
;         float rs[8];
; #pragma unroll
;         for (int g = 0; g < 8; ++g) rs[g] = ss2[row0 + (g >> 2) * 128 + (g & 3) * 16];
.LBB0_1048:
	v_lshl_add_u32 v230, s0, 8, v146
	v_ashrrev_i32_e32 v231, 31, v230
	v_lshl_add_u64 v[230:231], v[230:231], 2, s[88:89]
	global_load_dword v232, v[230:231], off
	global_load_dword v233, v[230:231], off offset:64
	global_load_dword v234, v[230:231], off offset:128
	global_load_dword v235, v[230:231], off offset:192
	global_load_dword v236, v[230:231], off offset:512
	global_load_dword v237, v[230:231], off offset:576
	global_load_dword v238, v[230:231], off offset:640
	global_load_dword v239, v[230:231], off offset:704
	s_add_i32 s44, s44, 1
	s_mul_i32 s6, s44, s48
	s_mul_hi_u32 s7, s44, s49
	s_add_i32 s7, s7, s6
	s_mul_i32 s6, s44, s49
	s_add_u32 s10, s6, s66
	s_addc_u32 s11, s7, s38
	v_cmp_gt_i64_e32 vcc, s[10:11], v[142:143]
	v_cmp_lt_i64_e64 s[6:7], s[10:11], v[140:141]
	s_cbranch_vccnz .LBB0_1050
	s_ashr_i32 s11, s10, 31
	s_lshr_b32 s11, s11, 29
	s_add_i32 s11, s10, s11
	s_ashr_i32 s12, s11, 3
	s_and_b32 s11, s11, -8
	s_sub_i32 s10, s10, s11
	s_cmp_lt_i32 s10, 0
	s_cselect_b32 s11, s39, 0x160
	s_mul_i32 s10, s10, s11
	s_add_i32 s10, s10, s12
	s_mul_hi_i32 s11, s10, 0x2e8ba2e9
	s_lshr_b32 s12, s11, 31
	s_ashr_i32 s11, s11, 6
	s_add_i32 s11, s11, s12
	s_lshl_b32 s12, s11, 3
	s_sub_i32 s13, 64, s12
	s_min_i32 s13, s13, 8
	s_abs_i32 s14, s13
	v_cvt_f32_u32_e32 v0, s14
	s_sub_i32 s16, 0, s14
	s_mulk_i32 s11, 0x160
	s_sub_i32 s10, s10, s11
	v_rcp_iflag_f32_e32 v0, v0
	s_abs_i32 s11, s10
	s_xor_b32 s15, s10, s13
	s_ashr_i32 s15, s15, 31
	v_mul_f32_e32 v0, 0x4f7ffffe, v0
	v_cvt_u32_f32_e32 v0, v0
	s_nop 0
	v_readfirstlane_b32 s17, v0
	s_mul_i32 s16, s16, s17
	s_mul_hi_u32 s16, s17, s16
	s_add_i32 s17, s17, s16
	s_mul_hi_u32 s16, s11, s17
	s_mul_i32 s17, s16, s14
	s_sub_i32 s11, s11, s17
	s_add_i32 s18, s16, 1
	s_sub_i32 s17, s11, s14
	s_cmp_ge_u32 s11, s14
	s_cselect_b32 s16, s18, s16
	s_cselect_b32 s11, s17, s11
	s_add_i32 s17, s16, 1
	s_cmp_ge_u32 s11, s14
	s_cselect_b32 s11, s17, s16
	s_xor_b32 s11, s11, s15
	s_sub_i32 s28, s11, s15
	s_mul_i32 s11, s28, s13
	s_sub_i32 s10, s10, s11
	s_add_i32 s30, s12, s10

; __device__ __forceinline__ unsigned pk2(float lo, float hi) { f32x2_t v = {lo, hi}; bf16x2_t b = __builtin_convertvector(v, bf16x2_t); return __builtin_bit_cast(unsigned, b); }
;     __device__ __forceinline__ void operator()(const pg8::f32x4 (&acc)[2][2][4][2], const pg8::Unit& u, int wr, int wc, int fr, int fq) const {
;         const int row0 = u.pm * 256 + wr * 64 + fr, col0 = u.pn * 256 + wc * 32 + 8 * fq;
;         float rs[8];
; #pragma unroll
;         for (int g = 0; g < 8; ++g) rs[g] = ss2[row0 + (g >> 2) * 128 + (g & 3) * 16];
; #pragma unroll
;         for (int g = 0; g < 8; ++g) rs[g] = rsqrtf(rs[g] * (1.f / 2048.f) + EPS);
;         const int sg = ((fq & 1) << 1) | (fq >> 1);
;         const bool up = fq >= 2;
; #pragma unroll
;         for (int ai = 0; ai < 2; ++ai)
; #pragma unroll
;             for (int mp = 0; mp < 2; ++mp) {
;                 const int rowA = row0 + ai * 128 + (2 * mp) * 16, rowB = rowA + 16;
;                 const float rA = rs[ai * 4 + 2 * mp], rB = rs[ai * 4 + 2 * mp + 1];
;                 const float rA2 = rA * rA, rB2 = rB * rB, rAl = rA * -1.4426950408889634f, rBl = rB * -1.4426950408889634f;
; #pragma unroll
;                 for (int bj = 0; bj < 2; ++bj) {
;                     const int ch = (col0 + bj * 128) >> 3, hc = 4 * ((ch & ~3) + sg);
;                     float oa[4], ob[4];
; #pragma unroll
;                     for (int i = 0; i < 4; ++i) {
;                         const float ga = acc[ai][bj][2 * mp][0][i], ua = acc[ai][bj][2 * mp][1][i];
;                         oa[i] = (ga * ua) * (rA2 * __builtin_amdgcn_rcpf(1.f + __builtin_amdgcn_exp2f(ga * rAl)));
;                         const float gb = acc[ai][bj][2 * mp + 1][0][i], ub = acc[ai][bj][2 * mp + 1][1][i];
;                         ob[i] = (gb * ub) * (rB2 * __builtin_amdgcn_rcpf(1.f + __builtin_amdgcn_exp2f(gb * rBl)));
;                     }
;                     unsigned ax = pk2(oa[0], oa[1]), ay = pk2(oa[2], oa[3]), bx = pk2(ob[0], ob[1]), by = pk2(ob[2], ob[3]);
;                     { auto rx = __builtin_amdgcn_permlane32_swap(ax, bx, false, false); ax = rx[0]; bx = rx[1]; }
;                     { auto ry = __builtin_amdgcn_permlane32_swap(ay, by, false, false); ay = ry[0]; by = ry[1]; }
;                     u32x4 o = {ax, ay, bx, by};
;                     *(u32x4*)(HH + (size_t)(up ? rowB : rowA) * DFF + (up ? hc - 4 : hc)) = o;
.LBB0_1054:
	v_lshl_add_u32 v144, s0, 8, v146
	s_lshl_b32 s0, s1, 8
	v_pk_mul_f32 v[154:155], v[112:113], v[120:121]
	v_or_b32_e32 v120, 16, v144
	s_or_b32 s0, s0, s45
	v_cndmask_b32_e64 v165, v144, v120, s[4:5]
	s_ashr_i32 s0, s0, 3
	v_or_b32_e32 v166, s0, v148
	v_pk_mul_f32 v[124:125], v[116:117], v[124:125]
	v_pk_mul_f32 v[126:127], v[118:119], v[126:127]
	v_pk_mul_f32 v[122:123], v[114:115], v[122:123]
	v_pk_mul_f32 v[110:111], v[102:103], v[110:111]
	v_pk_mul_f32 v[106:107], v[98:99], v[106:107]
	v_pk_mul_f32 v[94:95], v[86:87], v[94:95]
	v_pk_mul_f32 v[90:91], v[82:83], v[90:91]
	v_pk_mul_f32 v[78:79], v[70:71], v[78:79]
	v_pk_mul_f32 v[74:75], v[66:67], v[74:75]
	v_pk_mul_f32 v[62:63], v[54:55], v[62:63]
	v_pk_mul_f32 v[58:59], v[50:51], v[58:59]
	v_add_u32_e32 v163, 0x80, v144
	v_add_u32_e32 v164, 0x90, v144
	v_pk_mul_f32 v[46:47], v[38:39], v[46:47]
	v_pk_mul_f32 v[42:43], v[34:35], v[42:43]
	v_pk_mul_f32 v[30:31], v[22:23], v[30:31]
	v_pk_mul_f32 v[26:27], v[18:19], v[26:27]
	v_pk_mul_f32 v[6:7], v[2:3], v[6:7]
	v_pk_mul_f32 v[14:15], v[10:11], v[14:15]
	v_fmamk_f32 v120, v232, 0x3a000000, v153
	v_fmamk_f32 v121, v233, 0x3a000000, v153
	v_fmamk_f32 v145, v234, 0x3a000000, v153
	v_cmp_gt_f32_e32 vcc, s52, v120
	v_fmamk_f32 v157, v236, 0x3a000000, v153
	v_fmamk_f32 v156, v235, 0x3a000000, v153
	v_fmamk_f32 v159, v238, 0x3a000000, v153
	v_mul_f32_e32 v161, 0x4b800000, v120
	v_fmamk_f32 v158, v237, 0x3a000000, v153
	v_fmamk_f32 v160, v239, 0x3a000000, v153
	v_mul_f32_e32 v162, 0x4b800000, v121
	v_mul_f32_e32 v171, 0x4b800000, v159
	v_cndmask_b32_e32 v120, v120, v161, vcc
	v_cmp_gt_f32_e64 s[0:1], s52, v121
	v_cmp_gt_f32_e64 s[16:17], s52, v159
	v_mul_f32_e32 v172, 0x4b800000, v160
	v_cndmask_b32_e64 v121, v121, v162, s[0:1]
	v_cndmask_b32_e64 v159, v159, v171, s[16:17]
	v_cmp_gt_f32_e64 s[18:19], s52, v160
	v_rsq_f32_e32 v120, v120
	v_rsq_f32_e32 v121, v121
	v_cndmask_b32_e64 v160, v160, v172, s[18:19]
	v_rsq_f32_e32 v159, v159
	v_rsq_f32_e32 v160, v160
	v_mul_f32_e32 v161, 0x45800000, v120
	v_mul_f32_e32 v162, 0x45800000, v121
	v_mul_f32_e32 v171, 0x45800000, v159
	v_cndmask_b32_e32 v161, v120, v161, vcc
	v_mul_f32_e32 v167, 0x4b800000, v145
	v_mul_f32_e32 v168, 0x4b800000, v156
	v_mul_f32_e32 v170, 0x4b800000, v158
	v_cmp_gt_f32_e64 s[8:9], s52, v145
	v_cmp_gt_f32_e64 s[10:11], s52, v156
	v_cmp_gt_f32_e64 s[14:15], s52, v158
	v_mul_f32_e32 v172, 0x45800000, v160
	v_cndmask_b32_e64 v162, v121, v162, s[0:1]
	v_cndmask_b32_e64 v121, v159, v171, s[16:17]
	v_mul_f32_e32 v159, 0xbfb8aa3b, v161
	v_cndmask_b32_e64 v145, v145, v167, s[8:9]
	v_cndmask_b32_e64 v156, v156, v168, s[10:11]
	v_cndmask_b32_e64 v158, v158, v170, s[14:15]
	v_cndmask_b32_e64 v120, v160, v172, s[18:19]
	v_mul_f32_e32 v160, 0xbfb8aa3b, v162
	v_mul_f32_e32 v116, v116, v159
	v_mul_f32_e32 v117, v117, v159
	v_rsq_f32_e32 v145, v145
	v_rsq_f32_e32 v156, v156
	v_rsq_f32_e32 v158, v158
	v_mul_f32_e32 v112, v112, v160
	v_mul_f32_e32 v113, v113, v160
	v_exp_f32_e32 v116, v116
	v_exp_f32_e32 v117, v117
	v_mul_f32_e32 v169, 0x4b800000, v157
	v_cmp_gt_f32_e64 s[12:13], s52, v157
	v_exp_f32_e32 v112, v112
	v_exp_f32_e32 v113, v113
	v_cndmask_b32_e64 v157, v157, v169, s[12:13]
	v_rsq_f32_e32 v157, v157
	v_mul_f32_e32 v167, 0x45800000, v145
	v_mul_f32_e32 v168, 0x45800000, v156
	v_mul_f32_e32 v170, 0x45800000, v158
	v_add_f32_e32 v116, 1.0, v116
	v_add_f32_e32 v117, 1.0, v117
	v_cndmask_b32_e64 v145, v145, v167, s[8:9]
	v_cndmask_b32_e64 v167, v156, v168, s[10:11]
	v_cndmask_b32_e64 v168, v158, v170, s[14:15]
	v_mul_f32_e32 v156, v161, v161
	v_mul_f32_e32 v158, v162, v162
	v_add_f32_e32 v161, 1.0, v112
	v_add_f32_e32 v162, 1.0, v113
	v_rcp_f32_e32 v112, v116
	v_rcp_f32_e32 v113, v117
	v_mul_f32_e32 v169, 0x45800000, v157
	v_cndmask_b32_e64 v157, v157, v169, s[12:13]
	v_mul_f32_e32 v118, v118, v159
	v_mul_f32_e32 v119, v119, v159
	v_mul_f32_e32 v114, v114, v160
	v_exp_f32_e32 v118, v118
	v_pk_mul_f32 v[112:113], v[156:157], v[112:113] op_sel_hi:[0,1]
	v_exp_f32_e32 v119, v119
	v_mul_f32_e32 v115, v115, v160
	v_rcp_f32_e32 v116, v161
	v_exp_f32_e32 v161, v114
	v_pk_mul_f32 v[112:113], v[124:125], v[112:113]
	v_exp_f32_e32 v124, v115
	v_add_f32_e32 v114, 1.0, v118
	v_add_f32_e32 v115, 1.0, v119
	v_rcp_f32_e32 v117, v162
	v_rcp_f32_e32 v114, v114
	v_add_f32_e32 v118, 1.0, v161
	v_rcp_f32_e32 v115, v115
	v_add_f32_e32 v119, 1.0, v124
	v_rcp_f32_e32 v118, v118
	v_rcp_f32_e32 v119, v119
	v_pk_mul_f32 v[116:117], v[158:159], v[116:117] op_sel_hi:[0,1]
	v_pk_mul_f32 v[114:115], v[156:157], v[114:115] op_sel_hi:[0,1]
	v_pk_mul_f32 v[124:125], v[154:155], v[116:117]
	v_pk_mul_f32 v[114:115], v[126:127], v[114:115]
	v_pk_mul_f32 v[116:117], v[158:159], v[118:119] op_sel_hi:[0,1]
	v_lshlrev_b32_e32 v126, 2, v166
	v_pk_mul_f32 v[122:123], v[122:123], v[116:117]
	v_cvt_pk_bf16_f32 v117, v114, v115
	v_add_u32_e32 v114, -4, v126
	v_cndmask_b32_e64 v114, v126, v114, s[4:5]
	v_cvt_pk_bf16_f32 v116, v112, v113
	v_mov_b64_e32 v[112:113], s[68:69]
	v_ashrrev_i32_e32 v115, 31, v114
	v_cvt_pk_bf16_f32 v118, v124, v125
	v_cvt_pk_bf16_f32 v119, v122, v123
	v_mad_i64_i32 v[122:123], s[0:1], v165, s53, v[112:113]
	v_mul_f32_e32 v124, v100, v159
	v_lshlrev_b64 v[114:115], 1, v[114:115]
	v_permlane32_swap_b32_e32 v116, v118
	v_permlane32_swap_b32_e32 v117, v119
	v_exp_f32_e32 v127, v124
	v_lshl_add_u64 v[124:125], v[122:123], 0, v[114:115]
	global_store_dwordx4 v[124:125], v[116:119], off
	v_mul_f32_e32 v102, v102, v159
	v_mul_f32_e32 v98, v98, v160
	v_mul_f32_e32 v117, v96, v160
	v_exp_f32_e32 v117, v117
	v_mul_f32_e32 v118, v101, v159
	v_exp_f32_e32 v119, v118
	v_add_f32_e32 v116, 1.0, v127
; __device__ __forceinline__ unsigned pk2(float lo, float hi) { f32x2_t v = {lo, hi}; bf16x2_t b = __builtin_convertvector(v, bf16x2_t); return __builtin_bit_cast(unsigned, b); }
;     __device__ __forceinline__ void operator()(const pg8::f32x4 (&acc)[2][2][4][2], const pg8::Unit& u, int wr, int wc, int fr, int fq) const {
;     ...
;             for (int mp = 0; mp < 2; ++mp) {
;                 const int rowA = row0 + ai * 128 + (2 * mp) * 16, rowB = rowA + 16;
;                 const float rA = rs[ai * 4 + 2 * mp], rB = rs[ai * 4 + 2 * mp + 1];
;                 const float rA2 = rA * rA, rB2 = rB * rB, rAl = rA * -1.4426950408889634f, rBl = rB * -1.4426950408889634f;
; #pragma unroll
;                 for (int bj = 0; bj < 2; ++bj) {
;                     const int ch = (col0 + bj * 128) >> 3, hc = 4 * ((ch & ~3) + sg);
;                     float oa[4], ob[4];
; #pragma unroll
;                     for (int i = 0; i < 4; ++i) {
;                         const float ga = acc[ai][bj][2 * mp][0][i], ua = acc[ai][bj][2 * mp][1][i];
;                         oa[i] = (ga * ua) * (rA2 * __builtin_amdgcn_rcpf(1.f + __builtin_amdgcn_exp2f(ga * rAl)));
;                         const float gb = acc[ai][bj][2 * mp + 1][0][i], ub = acc[ai][bj][2 * mp + 1][1][i];
;                         ob[i] = (gb * ub) * (rB2 * __builtin_amdgcn_rcpf(1.f + __builtin_amdgcn_exp2f(gb * rBl)));
;                     }
;                     unsigned ax = pk2(oa[0], oa[1]), ay = pk2(oa[2], oa[3]), bx = pk2(ob[0], ob[1]), by = pk2(ob[2], ob[3]);
;                     { auto rx = __builtin_amdgcn_permlane32_swap(ax, bx, false, false); ax = rx[0]; bx = rx[1]; }
;                     { auto ry = __builtin_amdgcn_permlane32_swap(ay, by, false, false); ay = ry[0]; by = ry[1]; }
;                     u32x4 o = {ax, ay, bx, by};
;                     *(u32x4*)(HH + (size_t)(up ? rowB : rowA) * DFF + (up ? hc - 4 : hc)) = o;
	v_add_f32_e32 v117, 1.0, v117
	v_rcp_f32_e32 v118, v117
	v_add_f32_e32 v117, 1.0, v119
	v_rcp_f32_e32 v116, v116
	v_rcp_f32_e32 v117, v117
	v_mul_f32_e32 v119, v97, v160
	v_exp_f32_e32 v119, v119
	v_pk_mul_f32 v[100:101], v[100:101], v[108:109]
	v_pk_mul_f32 v[108:109], v[156:157], v[116:117] op_sel_hi:[0,1]
	v_pk_mul_f32 v[100:101], v[100:101], v[108:109]
	v_add_f32_e32 v108, 1.0, v119
	v_rcp_f32_e32 v119, v108
	v_exp_f32_e32 v102, v102
	v_exp_f32_e32 v108, v98
	v_mul_f32_e32 v103, v103, v159
	v_exp_f32_e32 v103, v103
	v_mul_f32_e32 v99, v99, v160
	v_add_f32_e32 v98, 1.0, v102
	v_add_f32_e32 v102, 1.0, v108
	v_exp_f32_e32 v108, v99
	v_add_f32_e32 v99, 1.0, v103
	v_rcp_f32_e32 v98, v98
	v_rcp_f32_e32 v99, v99
	v_add_f32_e32 v103, 1.0, v108
	v_rcp_f32_e32 v102, v102
	v_rcp_f32_e32 v103, v103
	v_pk_mul_f32 v[96:97], v[96:97], v[104:105]
	v_pk_mul_f32 v[104:105], v[158:159], v[118:119] op_sel_hi:[0,1]
	v_pk_mul_f32 v[98:99], v[156:157], v[98:99] op_sel_hi:[0,1]
	v_pk_mul_f32 v[96:97], v[96:97], v[104:105]
	v_pk_mul_f32 v[104:105], v[110:111], v[98:99]
	v_pk_mul_f32 v[98:99], v[158:159], v[102:103] op_sel_hi:[0,1]
	v_pk_mul_f32 v[102:103], v[106:107], v[98:99]
	v_or_b32_e32 v106, 64, v126
	v_cvt_pk_bf16_f32 v98, v100, v101
	v_cvt_pk_bf16_f32 v100, v96, v97
	v_add_u32_e32 v96, 60, v126
	v_cndmask_b32_e64 v96, v106, v96, s[4:5]
	v_ashrrev_i32_e32 v97, 31, v96
	v_cvt_pk_bf16_f32 v99, v104, v105
	v_cvt_pk_bf16_f32 v101, v102, v103
	v_lshlrev_b64 v[96:97], 1, v[96:97]
	v_permlane32_swap_b32_e32 v98, v100
	v_permlane32_swap_b32_e32 v99, v101
	v_lshl_add_u64 v[102:103], v[122:123], 0, v[96:97]
	global_store_dwordx4 v[102:103], v[98:101], off
	v_mul_f32_e32 v106, 0xbfb8aa3b, v167
	v_mul_f32_e32 v102, v80, v106
	v_mul_f32_e32 v99, 0xbfb8aa3b, v145
	v_mul_f32_e32 v100, v84, v99
	v_exp_f32_e32 v101, v100
	v_exp_f32_e32 v103, v102
	v_mul_f32_e32 v102, v85, v99
	v_exp_f32_e32 v105, v102
	v_add_f32_e32 v101, 1.0, v101
	v_rcp_f32_e32 v102, v101
	v_add_f32_e32 v101, 1.0, v103
	v_rcp_f32_e32 v104, v101
	v_add_f32_e32 v101, 1.0, v105
	v_rcp_f32_e32 v103, v101
	v_mul_f32_e32 v101, v81, v106
	v_exp_f32_e32 v101, v101
	v_mul_f32_e32 v98, v145, v145
	v_pk_mul_f32 v[84:85], v[84:85], v[92:93]
	v_pk_mul_f32 v[92:93], v[98:99], v[102:103] op_sel_hi:[0,1]
	v_pk_mul_f32 v[84:85], v[84:85], v[92:93]
	v_add_f32_e32 v92, 1.0, v101
	v_mul_f32_e32 v86, v86, v99
	v_mul_f32_e32 v82, v82, v106
	v_rcp_f32_e32 v105, v92
	v_exp_f32_e32 v86, v86
	v_exp_f32_e32 v92, v82
	v_mul_f32_e32 v87, v87, v99
	v_exp_f32_e32 v87, v87
	v_mul_f32_e32 v83, v83, v106
	v_add_f32_e32 v82, 1.0, v86
	v_add_f32_e32 v86, 1.0, v92
	v_exp_f32_e32 v92, v83
	v_add_f32_e32 v83, 1.0, v87
	v_rcp_f32_e32 v82, v82
	v_rcp_f32_e32 v83, v83
	v_add_f32_e32 v87, 1.0, v92
	v_rcp_f32_e32 v86, v86
	v_rcp_f32_e32 v87, v87
	v_mul_f32_e32 v100, v167, v167
	v_pk_mul_f32 v[80:81], v[80:81], v[88:89]
	v_pk_mul_f32 v[88:89], v[100:101], v[104:105] op_sel_hi:[0,1]
	v_pk_mul_f32 v[88:89], v[80:81], v[88:89]
	v_pk_mul_f32 v[80:81], v[98:99], v[82:83] op_sel_hi:[0,1]
	v_pk_mul_f32 v[82:83], v[94:95], v[80:81]
	v_pk_mul_f32 v[80:81], v[100:101], v[86:87] op_sel_hi:[0,1]
	v_or_b32_e32 v107, v144, v149
	v_pk_mul_f32 v[86:87], v[90:91], v[80:81]
	v_cvt_pk_bf16_f32 v80, v84, v85
	v_mul_f32_e32 v84, v68, v99
	v_cvt_pk_bf16_f32 v81, v82, v83
	v_cvt_pk_bf16_f32 v82, v88, v89
	v_cvt_pk_bf16_f32 v83, v86, v87
	v_exp_f32_e32 v88, v84
	v_mad_i64_i32 v[84:85], s[0:1], v107, s53, v[112:113]
	v_permlane32_swap_b32_e32 v80, v82
	v_permlane32_swap_b32_e32 v81, v83
	v_lshl_add_u64 v[86:87], v[84:85], 0, v[114:115]
	global_store_dwordx4 v[86:87], v[80:83], off
	v_mul_f32_e32 v70, v70, v99
	v_mul_f32_e32 v66, v66, v106
	v_mul_f32_e32 v81, v64, v106
	v_exp_f32_e32 v81, v81
	v_mul_f32_e32 v82, v69, v99
	v_exp_f32_e32 v83, v82
	v_add_f32_e32 v80, 1.0, v88
	v_add_f32_e32 v81, 1.0, v81
	v_rcp_f32_e32 v82, v81
	v_add_f32_e32 v81, 1.0, v83
	v_rcp_f32_e32 v80, v80
	v_rcp_f32_e32 v81, v81
	v_mul_f32_e32 v83, v65, v106
	v_exp_f32_e32 v83, v83
	v_pk_mul_f32 v[68:69], v[68:69], v[76:77]
	v_pk_mul_f32 v[76:77], v[98:99], v[80:81] op_sel_hi:[0,1]
	v_pk_mul_f32 v[68:69], v[68:69], v[76:77]
	v_add_f32_e32 v76, 1.0, v83
	v_rcp_f32_e32 v83, v76
	v_exp_f32_e32 v70, v70
	v_exp_f32_e32 v76, v66
	v_mul_f32_e32 v71, v71, v99
	v_exp_f32_e32 v71, v71
	v_mul_f32_e32 v67, v67, v106
	v_add_f32_e32 v66, 1.0, v70
	v_add_f32_e32 v70, 1.0, v76
	v_exp_f32_e32 v76, v67
	v_add_f32_e32 v67, 1.0, v71
	v_rcp_f32_e32 v66, v66
	v_rcp_f32_e32 v67, v67
	v_add_f32_e32 v71, 1.0, v76
	v_rcp_f32_e32 v70, v70
	v_rcp_f32_e32 v71, v71
	v_pk_mul_f32 v[64:65], v[64:65], v[72:73]
	v_pk_mul_f32 v[72:73], v[100:101], v[82:83] op_sel_hi:[0,1]
	v_pk_mul_f32 v[72:73], v[64:65], v[72:73]
	v_pk_mul_f32 v[64:65], v[98:99], v[66:67] op_sel_hi:[0,1]
	v_pk_mul_f32 v[66:67], v[78:79], v[64:65]
	v_pk_mul_f32 v[64:65], v[100:101], v[70:71] op_sel_hi:[0,1]
	v_pk_mul_f32 v[70:71], v[74:75], v[64:65]
	v_cvt_pk_bf16_f32 v64, v68, v69
	v_cvt_pk_bf16_f32 v65, v66, v67
	v_cvt_pk_bf16_f32 v66, v72, v73
	v_cvt_pk_bf16_f32 v67, v70, v71
	s_nop 0
	v_permlane32_swap_b32_e32 v64, v66
	v_permlane32_swap_b32_e32 v65, v67
	v_lshl_add_u64 v[68:69], v[84:85], 0, v[96:97]
	global_store_dwordx4 v[68:69], v[64:67], off
	v_mul_f32_e32 v72, 0xbfb8aa3b, v168
	v_mul_f32_e32 v68, v48, v72
	v_mul_f32_e32 v65, 0xbfb8aa3b, v157
	v_mul_f32_e32 v66, v52, v65
	v_exp_f32_e32 v67, v66
	v_exp_f32_e32 v69, v68
	v_mul_f32_e32 v68, v53, v65
	v_exp_f32_e32 v71, v68
	v_add_f32_e32 v67, 1.0, v67
	v_rcp_f32_e32 v68, v67
	v_add_f32_e32 v67, 1.0, v69
	v_rcp_f32_e32 v70, v67
	v_add_f32_e32 v67, 1.0, v71
	v_rcp_f32_e32 v69, v67
	v_mul_f32_e32 v67, v49, v72
; __device__ __forceinline__ unsigned pk2(float lo, float hi) { f32x2_t v = {lo, hi}; bf16x2_t b = __builtin_convertvector(v, bf16x2_t); return __builtin_bit_cast(unsigned, b); }
;     __device__ __forceinline__ void operator()(const pg8::f32x4 (&acc)[2][2][4][2], const pg8::Unit& u, int wr, int wc, int fr, int fq) const {
;     ...
;             for (int mp = 0; mp < 2; ++mp) {
;                 const int rowA = row0 + ai * 128 + (2 * mp) * 16, rowB = rowA + 16;
;                 const float rA = rs[ai * 4 + 2 * mp], rB = rs[ai * 4 + 2 * mp + 1];
;                 const float rA2 = rA * rA, rB2 = rB * rB, rAl = rA * -1.4426950408889634f, rBl = rB * -1.4426950408889634f;
; #pragma unroll
;                 for (int bj = 0; bj < 2; ++bj) {
;                     const int ch = (col0 + bj * 128) >> 3, hc = 4 * ((ch & ~3) + sg);
;                     float oa[4], ob[4];
; #pragma unroll
;                     for (int i = 0; i < 4; ++i) {
;                         const float ga = acc[ai][bj][2 * mp][0][i], ua = acc[ai][bj][2 * mp][1][i];
;                         oa[i] = (ga * ua) * (rA2 * __builtin_amdgcn_rcpf(1.f + __builtin_amdgcn_exp2f(ga * rAl)));
;                         const float gb = acc[ai][bj][2 * mp + 1][0][i], ub = acc[ai][bj][2 * mp + 1][1][i];
;                         ob[i] = (gb * ub) * (rB2 * __builtin_amdgcn_rcpf(1.f + __builtin_amdgcn_exp2f(gb * rBl)));
;                     }
;                     unsigned ax = pk2(oa[0], oa[1]), ay = pk2(oa[2], oa[3]), bx = pk2(ob[0], ob[1]), by = pk2(ob[2], ob[3]);
;                     { auto rx = __builtin_amdgcn_permlane32_swap(ax, bx, false, false); ax = rx[0]; bx = rx[1]; }
;                     { auto ry = __builtin_amdgcn_permlane32_swap(ay, by, false, false); ay = ry[0]; by = ry[1]; }
;                     u32x4 o = {ax, ay, bx, by};
;                     *(u32x4*)(HH + (size_t)(up ? rowB : rowA) * DFF + (up ? hc - 4 : hc)) = o;
	v_exp_f32_e32 v67, v67
	v_mul_f32_e32 v64, v157, v157
	v_pk_mul_f32 v[52:53], v[52:53], v[60:61]
	v_pk_mul_f32 v[60:61], v[64:65], v[68:69] op_sel_hi:[0,1]
	v_pk_mul_f32 v[52:53], v[52:53], v[60:61]
	v_add_f32_e32 v60, 1.0, v67
	v_mul_f32_e32 v54, v54, v65
	v_mul_f32_e32 v50, v50, v72
	v_rcp_f32_e32 v71, v60
	v_exp_f32_e32 v54, v54
	v_exp_f32_e32 v60, v50
	v_mul_f32_e32 v55, v55, v65
	v_exp_f32_e32 v55, v55
	v_mul_f32_e32 v51, v51, v72
	v_add_f32_e32 v50, 1.0, v54
	v_add_f32_e32 v54, 1.0, v60
	v_exp_f32_e32 v60, v51
	v_add_f32_e32 v51, 1.0, v55
	v_rcp_f32_e32 v50, v50
	v_rcp_f32_e32 v51, v51
	v_add_f32_e32 v55, 1.0, v60
	v_rcp_f32_e32 v54, v54
	v_rcp_f32_e32 v55, v55
	v_mul_f32_e32 v66, v168, v168
	v_pk_mul_f32 v[48:49], v[48:49], v[56:57]
	v_pk_mul_f32 v[56:57], v[66:67], v[70:71] op_sel_hi:[0,1]
	v_pk_mul_f32 v[56:57], v[48:49], v[56:57]
	v_pk_mul_f32 v[48:49], v[64:65], v[50:51] op_sel_hi:[0,1]
	v_pk_mul_f32 v[50:51], v[62:63], v[48:49]
	v_pk_mul_f32 v[48:49], v[66:67], v[54:55] op_sel_hi:[0,1]
	v_cndmask_b32_e64 v73, v163, v164, s[4:5]
	v_pk_mul_f32 v[54:55], v[58:59], v[48:49]
	v_cvt_pk_bf16_f32 v48, v52, v53
	v_mul_f32_e32 v52, v36, v65
	v_cvt_pk_bf16_f32 v49, v50, v51
	v_cvt_pk_bf16_f32 v50, v56, v57
	v_cvt_pk_bf16_f32 v51, v54, v55
	v_exp_f32_e32 v56, v52
	v_mad_i64_i32 v[52:53], s[0:1], v73, s53, v[112:113]
	v_permlane32_swap_b32_e32 v48, v50
	v_permlane32_swap_b32_e32 v49, v51
	v_lshl_add_u64 v[54:55], v[52:53], 0, v[114:115]
	global_store_dwordx4 v[54:55], v[48:51], off
	v_mul_f32_e32 v38, v38, v65
	v_mul_f32_e32 v34, v34, v72
	v_mul_f32_e32 v49, v32, v72
	v_exp_f32_e32 v49, v49
	v_mul_f32_e32 v50, v37, v65
	v_exp_f32_e32 v51, v50
	v_add_f32_e32 v48, 1.0, v56
	v_add_f32_e32 v49, 1.0, v49
	v_rcp_f32_e32 v50, v49
	v_add_f32_e32 v49, 1.0, v51
	v_rcp_f32_e32 v48, v48
	v_rcp_f32_e32 v49, v49
	v_mul_f32_e32 v51, v33, v72
	v_exp_f32_e32 v51, v51
	v_pk_mul_f32 v[36:37], v[36:37], v[44:45]
	v_pk_mul_f32 v[44:45], v[64:65], v[48:49] op_sel_hi:[0,1]
	v_pk_mul_f32 v[36:37], v[36:37], v[44:45]
	v_add_f32_e32 v44, 1.0, v51
	v_rcp_f32_e32 v51, v44
	v_exp_f32_e32 v38, v38
	v_exp_f32_e32 v44, v34
	v_mul_f32_e32 v39, v39, v65
	v_exp_f32_e32 v39, v39
	v_mul_f32_e32 v35, v35, v72
	v_add_f32_e32 v34, 1.0, v38
	v_add_f32_e32 v38, 1.0, v44
	v_exp_f32_e32 v44, v35
	v_add_f32_e32 v35, 1.0, v39
	v_rcp_f32_e32 v34, v34
	v_rcp_f32_e32 v35, v35
	v_add_f32_e32 v39, 1.0, v44
	v_rcp_f32_e32 v38, v38
	v_rcp_f32_e32 v39, v39
	v_pk_mul_f32 v[32:33], v[32:33], v[40:41]
	v_pk_mul_f32 v[40:41], v[66:67], v[50:51] op_sel_hi:[0,1]
	v_pk_mul_f32 v[40:41], v[32:33], v[40:41]
	v_pk_mul_f32 v[32:33], v[64:65], v[34:35] op_sel_hi:[0,1]
	v_pk_mul_f32 v[34:35], v[46:47], v[32:33]
	v_pk_mul_f32 v[32:33], v[66:67], v[38:39] op_sel_hi:[0,1]
	v_pk_mul_f32 v[38:39], v[42:43], v[32:33]
	v_cvt_pk_bf16_f32 v32, v36, v37
	v_cvt_pk_bf16_f32 v33, v34, v35
	v_cvt_pk_bf16_f32 v34, v40, v41
	v_cvt_pk_bf16_f32 v35, v38, v39
	s_nop 0
	v_permlane32_swap_b32_e32 v32, v34
	v_permlane32_swap_b32_e32 v33, v35
	v_lshl_add_u64 v[36:37], v[52:53], 0, v[96:97]
	v_mul_f32_e32 v40, 0xbfb8aa3b, v121
	global_store_dwordx4 v[36:37], v[32:35], off
	v_mul_f32_e32 v41, 0xbfb8aa3b, v120
	v_mul_f32_e32 v22, v22, v40
	v_mul_f32_e32 v34, v20, v40
	v_exp_f32_e32 v36, v34
	v_add_u32_e32 v33, 0xa0, v144
	v_add_u32_e32 v35, 0xb0, v144
	v_cndmask_b32_e64 v33, v33, v35, s[4:5]
	v_add_f32_e32 v35, 1.0, v36
	v_mul_f32_e32 v36, v16, v41
	v_exp_f32_e32 v37, v36
	v_mul_f32_e32 v36, v21, v40
	v_exp_f32_e32 v39, v36
	v_rcp_f32_e32 v36, v35
	v_add_f32_e32 v35, 1.0, v37
	v_rcp_f32_e32 v38, v35
	v_add_f32_e32 v35, 1.0, v39
	v_rcp_f32_e32 v37, v35
	v_mul_f32_e32 v35, v17, v41
	v_exp_f32_e32 v35, v35
	v_mul_f32_e32 v32, v121, v121
	v_pk_mul_f32 v[20:21], v[20:21], v[28:29]
	v_pk_mul_f32 v[28:29], v[32:33], v[36:37] op_sel_hi:[0,1]
	v_pk_mul_f32 v[20:21], v[20:21], v[28:29]
	v_add_f32_e32 v28, 1.0, v35
	v_mul_f32_e32 v18, v18, v41
	v_rcp_f32_e32 v39, v28
	v_exp_f32_e32 v22, v22
	v_exp_f32_e32 v28, v18
	v_mul_f32_e32 v23, v23, v40
	v_exp_f32_e32 v23, v23
	v_mul_f32_e32 v19, v19, v41
	v_add_f32_e32 v18, 1.0, v22
	v_add_f32_e32 v22, 1.0, v28
	v_exp_f32_e32 v28, v19
	v_add_f32_e32 v19, 1.0, v23
	v_rcp_f32_e32 v18, v18
	v_rcp_f32_e32 v19, v19
	v_add_f32_e32 v23, 1.0, v28
	v_rcp_f32_e32 v22, v22
	v_rcp_f32_e32 v23, v23
	v_mul_f32_e32 v34, v120, v120
	v_pk_mul_f32 v[16:17], v[16:17], v[24:25]
	v_pk_mul_f32 v[24:25], v[34:35], v[38:39] op_sel_hi:[0,1]
	v_pk_mul_f32 v[24:25], v[16:17], v[24:25]
	v_pk_mul_f32 v[16:17], v[32:33], v[18:19] op_sel_hi:[0,1]
	v_pk_mul_f32 v[18:19], v[30:31], v[16:17]
	v_pk_mul_f32 v[16:17], v[34:35], v[22:23] op_sel_hi:[0,1]
	v_pk_mul_f32 v[22:23], v[26:27], v[16:17]
	v_cvt_pk_bf16_f32 v16, v20, v21
	v_mul_f32_e32 v20, v8, v40
	v_cvt_pk_bf16_f32 v17, v18, v19
	v_cvt_pk_bf16_f32 v18, v24, v25
	v_cvt_pk_bf16_f32 v19, v22, v23
	v_exp_f32_e32 v24, v20
	v_mad_i64_i32 v[20:21], s[0:1], v33, s53, v[112:113]
	v_permlane32_swap_b32_e32 v16, v18
	v_permlane32_swap_b32_e32 v17, v19
	v_lshl_add_u64 v[22:23], v[20:21], 0, v[114:115]
	global_store_dwordx4 v[22:23], v[16:19], off
	v_mul_f32_e32 v2, v2, v41
	v_mul_f32_e32 v11, v11, v40
	v_mul_f32_e32 v17, v0, v41
	v_exp_f32_e32 v17, v17
	v_mul_f32_e32 v18, v9, v40
	v_exp_f32_e32 v19, v18
	v_add_f32_e32 v16, 1.0, v24
	v_add_f32_e32 v17, 1.0, v17
	v_rcp_f32_e32 v18, v17
	v_add_f32_e32 v17, 1.0, v19
	v_rcp_f32_e32 v16, v16
	v_rcp_f32_e32 v17, v17
	v_mul_f32_e32 v19, v1, v41
	v_exp_f32_e32 v19, v19
	v_pk_mul_f32 v[8:9], v[8:9], v[12:13]
	v_pk_mul_f32 v[12:13], v[32:33], v[16:17] op_sel_hi:[0,1]
	v_pk_mul_f32 v[8:9], v[8:9], v[12:13]
	v_add_f32_e32 v12, 1.0, v19
	v_pk_mul_f32 v[0:1], v[0:1], v[4:5]
	v_mul_f32_e32 v4, v10, v40
	v_rcp_f32_e32 v19, v12
	v_exp_f32_e32 v10, v4
	v_exp_f32_e32 v12, v2
	v_exp_f32_e32 v11, v11
	v_mul_f32_e32 v3, v3, v41
	v_add_f32_e32 v2, 1.0, v10
	v_add_f32_e32 v10, 1.0, v12
	v_exp_f32_e32 v12, v3
	v_add_f32_e32 v3, 1.0, v11
	v_rcp_f32_e32 v2, v2
	v_rcp_f32_e32 v3, v3
	v_add_f32_e32 v11, 1.0, v12
	v_rcp_f32_e32 v10, v10
	v_rcp_f32_e32 v11, v11
	v_pk_mul_f32 v[4:5], v[34:35], v[18:19] op_sel_hi:[0,1]
	v_pk_mul_f32 v[4:5], v[0:1], v[4:5]
	v_pk_mul_f32 v[0:1], v[32:33], v[2:3] op_sel_hi:[0,1]
	v_pk_mul_f32 v[2:3], v[14:15], v[0:1]
	v_pk_mul_f32 v[0:1], v[34:35], v[10:11] op_sel_hi:[0,1]
	v_pk_mul_f32 v[6:7], v[6:7], v[0:1]
	v_cvt_pk_bf16_f32 v0, v8, v9
	v_cvt_pk_bf16_f32 v1, v2, v3
	v_cvt_pk_bf16_f32 v2, v4, v5
	v_cvt_pk_bf16_f32 v3, v6, v7
	s_nop 0
	v_permlane32_swap_b32_e32 v0, v2
	v_permlane32_swap_b32_e32 v1, v3
	v_lshl_add_u64 v[4:5], v[20:21], 0, v[96:97]
	s_andn2_b64 vcc, exec, s[6:7]
	s_mov_b64 s[0:1], -1
	global_store_dwordx4 v[4:5], v[0:3], off
	s_cbranch_vccnz .LBB0_1047
	s_andn2_b64 vcc, exec, s[22:23]
	s_cbranch_vccnz .LBB0_1046
	s_barrier
	s_branch .LBB0_1046
